# v16: attention V tiles staged HBM->LDS directly (global_load_lds_dwordx4), K still register-staged
# speedup vs baseline: 1.0105x; 1.0105x over previous
; __device__ void phase_attn(const Params& p, char* lds) {
;     ...
;   const bf16_t* Qg = (const bf16_t*)(ws + OFF_Q); const bf16_t* KVg = (const bf16_t*)(ws + OFF_KV); const bf16_t* KPg = (const bf16_t*)(ws + OFF_KPE);
;   bf16_t* G1 = (bf16_t*)(ws + OFF_G1);
;   const f32x2* rope = (const f32x2*)(ws + OFF_ROPE);
;   const int tid = threadIdx.x, wid = tid >> 6, lane = tid & 63, r32 = lane & 31, hi = lane >> 5;
;   char* V_lds = lds; char* K_lds = lds + AT_KOFF;
;   float* wsl = (float*)(lds + AT_WOFF) + wid * 64; float* li_l = wsl; float* al_l = wsl + 32;
;   const int skey = tid >> 3, sc8 = (tid & 7) * 8;
;   const int pkey = (tid & 255) >> 2, pc8 = (tid & 3) * 8;
;   const int vst = v_st(skey, sc8), kst = skey * AT_KROW + sc8 * 2, pst = pkey * AT_KROW + (64 + pc8) * 2;
;   const int vb0 = (int)(uintptr_t)V_lds + v_rd_base(lane);
;   const int nitems = NB * 16 * 32;
;   const int xcd = blockIdx.x & 7, slot = blockIdx.x >> 3, per = gridDim.x >> 3;
;   for (int it = slot; it < nitems / 8; it += per) {
;     const int pair = (it >> 5) * 8 + xcd, qblk = it & 31;
;     const int b = pair >> 4, h = pair & 15;
;     const size_t row0 = (size_t)b * TL;
;     const size_t qrow = row0 + qblk * 256 + wid * 32 + r32;
;     const bf16_t* Kh = KVg + row0 * 2048 + h * 128;
;     const bf16_t* Kp = KPg + row0 * 32;
;     float m_reg = 0.f, l_reg = 0.f;
;     f32x16 o[2];
; #pragma unroll
;     for (int dd = 0; dd < 2; ++dd)
; #pragma unroll
;       for (int r = 0; r < 16; ++r) o[dd][r] = 0.f;
;     bf16x8 qr[6];
;     {
;       const bf16_t* Qw = Qg + qrow * 1536 + h * 96 + hi * 8;
; #pragma unroll
;       for (int d0 = 0; d0 < 6; ++d0) qr[d0] = *(const bf16x8*)(Qw + d0 * 16);
;       const int t = qblk * 256 + wid * 32 + r32;
;       const f32x2* tb = rope + (hi ? (t & 63) : (t >> 6)) * 8;
;       const u32x4 x1 = *(const u32x4*)&qr[4], x2 = *(const u32x4*)&qr[5];
;       u32x4 n1, n2;
; #pragma unroll
;       for (int q = 0; q < 4; ++q) {
;         const f32x2 csA = tb[2 * q], csB = tb[2 * q + 1];
;         const float a0 = lo16(x1[q]), a1 = hi16(x1[q]), b0 = lo16(x2[q]), b1 = hi16(x2[q]);
;         n1[q] = cvtpk(a0 * csA[0] - b0 * csA[1], a1 * csB[0] - b1 * csB[1]);
;         n2[q] = cvtpk(a0 * csA[1] + b0 * csA[0], a1 * csB[1] + b1 * csB[0]);
;       }
;       qr[4] = *(bf16x8*)&n1; qr[5] = *(bf16x8*)&n2;
;     }
;     struct { bf16x8 vs, ks, ps; } sr_[2];
.LBB0_991:
	s_or_b64 exec, exec, s[4:5]
	s_cmpk_gt_u32 s3, 0xfff
	s_waitcnt vmcnt(7)
	v_and_b32_e32 v128, 56, v183
	v_lshlrev_b32_e32 v168, 11, v161
	s_barrier
	v_and_b32_e32 v175, 63, v178
	v_and_b32_e32 v183, 31, v178
	v_lshrrev_b32_e32 v228, 5, v175
	v_readfirstlane_b32 s14, v178
	v_lshrrev_b32_e32 v229, 3, v178
	v_and_b32_e32 v230, 7, v178
	s_lshr_b32 s14, s14, 6
	s_lshr_b32 s15, s14, 2
	s_and_b32 s43, s3, 7
	s_mov_b32 s23, 0x453a4f54
	v_lshlrev_b32_e32 v129, 4, v230
	v_lshl_or_b32 v129, v229, 12, v129
	v_mul_u32_u24_e32 v167, 0xd0, v229
	v_lshl_add_u32 v167, v230, 4, v167
	v_add_u32_e32 v167, 0x10000, v167
	v_bfe_u32 v131, v175, 2, 3
	v_lshl_add_u32 v131, s14, 3, v131
	v_lshlrev_b32_e32 v131, 12, v131
	v_lshlrev_b32_e32 v174, 2, v228
	v_and_or_b32 v174, v175, 3, v174
	v_lshl_add_u32 v131, v174, 4, v131
	v_add_u32_e32 v131, 0x80, v131
	s_lshl_b32 s40, s14, 11
	v_and_b32_e32 v174, 3, v178
	v_bfe_u32 v229, v178, 2, 6
	v_lshlrev_b32_e32 v130, 4, v174
	v_lshl_or_b32 v130, v229, 6, v130
	v_mul_u32_u24_e32 v169, 0xd0, v229
	v_lshl_add_u32 v169, v174, 4, v169
	v_add_u32_e32 v169, 0x10080, v169
	v_mul_u32_u24_e32 v170, 0xd0, v183
	v_lshl_add_u32 v170, v228, 4, v170
	v_add_u32_e32 v170, 0x10000, v170
	v_and_b32_e32 v174, 3, v175
	v_lshlrev_b32_e32 v174, 3, v174
	v_mov_b32_e32 v171, v174
	v_bfe_u32 v174, v175, 2, 2
	v_lshl_or_b32 v171, v174, 6, v171
	v_bfe_u32 v174, v175, 4, 1
	v_lshl_or_b32 v171, v174, 5, v171
	v_lshl_or_b32 v171, v228, 8, v171
	s_lshl_b32 s16, s14, 5
	v_add_u32_e32 v174, s16, v183
	v_mul_u32_u24_e32 v234, 0xc00, v174
	v_lshl_add_u32 v234, v228, 4, v234
	v_lshlrev_b32_e32 v235, 2, v228
	v_add_u32_e32 v235, s16, v235
	v_lshlrev_b32_e32 v235, 11, v235
	v_lshl_add_u32 v235, v183, 1, v235
	s_lshl_b32 s17, s14, 8
	s_add_i32 s17, s17, 0x1d000
	v_lshl_add_u32 v244, v183, 2, s17
	v_lshl_add_u32 v245, v228, 4, s17
	s_add_u32 s34, s86, 0x3d796000
	s_addc_u32 s35, s87, 0
	s_lshr_b32 s12, s3, 3
.Lat_item:
	s_lshr_b32 s16, s12, 5
	s_lshl_b32 s16, s16, 3
	s_add_i32 s16, s16, s43
	s_and_b32 s20, s12, 31
	s_lshr_b32 s22, s16, 4
	s_and_b32 s21, s16, 15
	s_mul_i32 s17, s22, 0x2100000
	s_lshl_b32 s18, s21, 8
	s_add_i32 s17, s17, s18
	s_add_u32 s17, s17, 0x29400000
	s_add_u32 s4, s86, s17
	s_addc_u32 s5, s87, 0
	s_mul_i32 s17, s22, 0x84000
	s_add_u32 s17, s17, 0x1de80000
	s_add_u32 s6, s86, s17
	s_addc_u32 s7, s87, 0
	s_mul_i32 s17, s22, 0x2100
	s_lshl_b32 s18, s20, 8
	s_add_i32 s17, s17, s18
	s_mul_i32 s18, s17, 0xc00
	s_mul_i32 s19, s21, 0xc0
	s_add_i32 s18, s18, s19
	s_add_u32 s18, s18, 0x8400000
	s_add_u32 s10, s86, s18
	s_addc_u32 s11, s87, 0
	s_lshl_b32 s18, s17, 11
	s_lshl_b32 s19, s21, 7
	s_add_i32 s18, s18, s19
	s_add_u32 s18, s18, 0x21000000
	s_add_u32 s28, s86, s18
	s_addc_u32 s29, s87, 0
	global_load_dwordx4 v[80:83], v234, s[10:11] offset:0
	global_load_dwordx4 v[84:87], v234, s[10:11] offset:32
	global_load_dwordx4 v[88:91], v234, s[10:11] offset:64
	global_load_dwordx4 v[92:95], v234, s[10:11] offset:96
	global_load_dwordx4 v[96:99], v234, s[10:11] offset:128
	global_load_dwordx4 v[100:103], v234, s[10:11] offset:160
	s_and_b32 s16, s14, 1
	s_lshl_b32 s16, s16, 5
	v_and_b32_e32 v183, 31, v178
	v_add_u32_e32 v183, s16, v183
	v_lshlrev_b32_e32 v183, 6, v183
	s_lshl_b32 s16, s20, 2
	s_lshr_b32 s17, s14, 1
	s_add_i32 s16, s16, s17
	s_lshl_b32 s16, s16, 6
	v_mov_b32_e32 v228, s16
	v_and_b32_e32 v229, 32, v178
	v_cmp_ne_u32_e32 vcc, 0, v229
	s_nop 1
	v_cndmask_b32_e32 v183, v228, v183, vcc
	global_load_dwordx4 v[32:35], v183, s[34:35] offset:0
	global_load_dwordx4 v[36:39], v183, s[34:35] offset:16
	global_load_dwordx4 v[40:43], v183, s[34:35] offset:32
	global_load_dwordx4 v[44:47], v183, s[34:35] offset:48
	s_barrier
	s_mov_b64 s[36:37], s[4:5]
	s_add_i32 m0, s40, 0x0
	s_nop 0
	global_load_lds_dwordx4 v131, s[36:37]
	s_add_u32 s36, s36, 0x40000
	s_addc_u32 s37, s37, 0
	s_add_i32 m0, s40, 0x4000
	s_nop 0
	global_load_lds_dwordx4 v131, s[36:37]
	s_add_u32 s36, s36, 0x40000
	s_addc_u32 s37, s37, 0
	global_load_dwordx4 v[120:123], v129, s[4:5]
	global_load_dwordx4 v[132:135], v130, s[6:7]
	s_add_u32 s4, s4, 0x40000
	s_addc_u32 s5, s5, 0
	s_add_u32 s6, s6, 0x1000
	s_addc_u32 s7, s7, 0
	global_load_dwordx4 v[136:139], v129, s[4:5]
	global_load_dwordx4 v[144:147], v130, s[6:7]
	s_add_u32 s4, s4, 0x40000
	s_addc_u32 s5, s5, 0
	s_add_u32 s6, s6, 0x1000
	s_addc_u32 s7, s7, 0
	s_waitcnt vmcnt(0)
	ds_write_b128 v167, v[120:123] offset:0
	ds_write_b128 v169, v[132:135] offset:0
	ds_write_b128 v167, v[136:139] offset:13312
	ds_write_b128 v169, v[144:147] offset:13312
	s_waitcnt lgkmcnt(0)
; __device__ __forceinline__ void at_partialSM(f32x16& p0, f32x16& p1, float& m_reg, float& alpha, bool force) {
;   float pm = p0[0];
; #pragma unroll
;   for (int r = 1; r < 16; ++r) pm = fmaxf(pm, p0[r]);
; #pragma unroll
;   for (int r = 0; r < 16; ++r) pm = fmaxf(pm, p1[r]);
;   { auto rr = __builtin_amdgcn_permlane32_swap(__float_as_uint(pm), __float_as_uint(pm), false, false);
;     pm = fmaxf(__uint_as_float(rr[0]), __uint_as_float(rr[1])); }
;   if (__builtin_expect(!force && __all(pm <= AT_THR * 1.4426950408889634f), 1)) { alpha = 1.f; }
;   else {
;     const float dlt = force ? pm : fmaxf(pm, 0.f);
;     alpha = force ? 1.f : __builtin_amdgcn_exp2f(-dlt); m_reg += dlt;
; #pragma unroll
;     for (int r = 0; r < 16; ++r) { p0[r] -= dlt; p1[r] -= dlt; }
;   }
; #pragma unroll
;   for (int r = 0; r < 16; ++r) p0[r] = __builtin_amdgcn_exp2f(p0[r]);
; }
; __device__ __forceinline__ void at_finishSM(f32x16& p0, f32x16& p1, float alpha, float& l_reg, bf16x8& pa0, bf16x8& pa1, bf16x8& pa2, bf16x8& pa3) {
; #pragma unroll
;   for (int r = 0; r < 16; ++r) p1[r] = __builtin_amdgcn_exp2f(p1[r]);
;   float ps = 0;
; #pragma unroll
;   for (int r = 0; r < 16; ++r) ps += p0[r];
; #pragma unroll
;   for (int r = 0; r < 16; ++r) ps += p1[r];
;   { auto rr = __builtin_amdgcn_permlane32_swap(__float_as_uint(ps), __float_as_uint(ps), false, false);
; __device__ void phase_attn(const Params& p, char* lds) {
;     ...
;     f32x16 o[2];
; #pragma unroll
;     for (int dd = 0; dd < 2; ++dd)
; #pragma unroll
;       for (int r = 0; r < 16; ++r) o[dd][r] = 0.f;
;     bf16x8 qr[6];
;     {
;       const bf16_t* Qw = Qg + qrow * 1536 + h * 96 + hi * 8;
; #pragma unroll
;       for (int d0 = 0; d0 < 6; ++d0) qr[d0] = *(const bf16x8*)(Qw + d0 * 16);
;       const int t = qblk * 256 + wid * 32 + r32;
;       const f32x2* tb = rope + (hi ? (t & 63) : (t >> 6)) * 8;
;       const u32x4 x1 = *(const u32x4*)&qr[4], x2 = *(const u32x4*)&qr[5];
;       u32x4 n1, n2;
; #pragma unroll
;       for (int q = 0; q < 4; ++q) {
;         const f32x2 csA = tb[2 * q], csB = tb[2 * q + 1];
;         const float a0 = lo16(x1[q]), a1 = hi16(x1[q]), b0 = lo16(x2[q]), b1 = hi16(x2[q]);
;         n1[q] = cvtpk(a0 * csA[0] - b0 * csA[1], a1 * csB[0] - b1 * csB[1]);
;         n2[q] = cvtpk(a0 * csA[1] + b0 * csA[0], a1 * csB[1] + b1 * csB[0]);
;       }
;       qr[4] = *(bf16x8*)&n1; qr[5] = *(bf16x8*)&n2;
	global_load_dwordx4 v[120:123], v129, s[4:5]
	global_load_dwordx4 v[132:135], v130, s[6:7]
	s_add_u32 s4, s4, 0x40000
	s_addc_u32 s5, s5, 0
	s_add_u32 s6, s6, 0x1000
	s_addc_u32 s7, s7, 0
	v_lshlrev_b32_e32 v175, 16, v96
	v_and_b32_e32 v183, 0xffff0000, v96
	v_lshlrev_b32_e32 v228, 16, v100
	v_and_b32_e32 v229, 0xffff0000, v100
	v_mul_f32_e32 v230, v228, v33
	v_mul_f32_e32 v174, v229, v35
	v_fma_f32 v230, v175, v32, -v230
	v_fma_f32 v174, v183, v34, -v174
	v_mul_f32_e32 v175, v175, v33
	v_mul_f32_e32 v183, v183, v35
	v_fma_f32 v175, v228, v32, v175
	v_fma_f32 v183, v229, v34, v183
	v_cvt_pk_bf16_f32 v96, v230, v174
	v_cvt_pk_bf16_f32 v100, v175, v183
	v_lshlrev_b32_e32 v175, 16, v97
	v_and_b32_e32 v183, 0xffff0000, v97
	v_lshlrev_b32_e32 v228, 16, v101
	v_and_b32_e32 v229, 0xffff0000, v101
	v_mul_f32_e32 v230, v228, v37
	v_mul_f32_e32 v174, v229, v39
	v_fma_f32 v230, v175, v36, -v230
	v_fma_f32 v174, v183, v38, -v174
	v_mul_f32_e32 v175, v175, v37
	v_mul_f32_e32 v183, v183, v39
	v_fma_f32 v175, v228, v36, v175
	v_fma_f32 v183, v229, v38, v183
	v_cvt_pk_bf16_f32 v97, v230, v174
	v_cvt_pk_bf16_f32 v101, v175, v183
	v_lshlrev_b32_e32 v175, 16, v98
	v_and_b32_e32 v183, 0xffff0000, v98
	v_lshlrev_b32_e32 v228, 16, v102
	v_and_b32_e32 v229, 0xffff0000, v102
	v_mul_f32_e32 v230, v228, v41
	v_mul_f32_e32 v174, v229, v43
	v_fma_f32 v230, v175, v40, -v230
	v_fma_f32 v174, v183, v42, -v174
	v_mul_f32_e32 v175, v175, v41
	v_mul_f32_e32 v183, v183, v43
	v_fma_f32 v175, v228, v40, v175
	v_fma_f32 v183, v229, v42, v183
	v_cvt_pk_bf16_f32 v98, v230, v174
	v_cvt_pk_bf16_f32 v102, v175, v183
	v_lshlrev_b32_e32 v175, 16, v99
	v_and_b32_e32 v183, 0xffff0000, v99
	v_lshlrev_b32_e32 v228, 16, v103
	v_and_b32_e32 v229, 0xffff0000, v103
	v_mul_f32_e32 v230, v228, v45
	v_mul_f32_e32 v174, v229, v47
	v_fma_f32 v230, v175, v44, -v230
	v_fma_f32 v174, v183, v46, -v174
	v_mul_f32_e32 v175, v175, v45
	v_mul_f32_e32 v183, v183, v47
	v_fma_f32 v175, v228, v44, v175
	v_fma_f32 v183, v229, v46, v183
	v_cvt_pk_bf16_f32 v99, v230, v174
	v_cvt_pk_bf16_f32 v103, v175, v183
	v_mov_b32_e32 v0, 0
	v_mov_b32_e32 v1, 0
	v_mov_b32_e32 v2, 0
	v_mov_b32_e32 v3, 0
	v_mov_b32_e32 v4, 0
	v_mov_b32_e32 v5, 0
	v_mov_b32_e32 v6, 0
	v_mov_b32_e32 v7, 0
	v_mov_b32_e32 v8, 0
	v_mov_b32_e32 v9, 0
	v_mov_b32_e32 v10, 0
	v_mov_b32_e32 v11, 0
	v_mov_b32_e32 v12, 0
	v_mov_b32_e32 v13, 0
	v_mov_b32_e32 v14, 0
	v_mov_b32_e32 v15, 0
	v_mov_b32_e32 v16, 0
	v_mov_b32_e32 v17, 0
	v_mov_b32_e32 v18, 0
	v_mov_b32_e32 v19, 0
	v_mov_b32_e32 v20, 0
	v_mov_b32_e32 v21, 0
	v_mov_b32_e32 v22, 0
	v_mov_b32_e32 v23, 0
	v_mov_b32_e32 v24, 0
	v_mov_b32_e32 v25, 0
	v_mov_b32_e32 v26, 0
	v_mov_b32_e32 v27, 0
	v_mov_b32_e32 v28, 0
	v_mov_b32_e32 v29, 0
	v_mov_b32_e32 v30, 0
	v_mov_b32_e32 v31, 0
	v_mov_b32_e32 v173, 0
	s_barrier
	ds_read_b128 v[184:187], v170 offset:0
	ds_read_b128 v[188:191], v170 offset:6656
	ds_read_b128 v[192:195], v170 offset:32
	ds_read_b128 v[196:199], v170 offset:6688
	s_cmp_eq_u32 s15, 0
	s_cbranch_scc1 .Lat_nostag
	s_barrier
.Lat_nostag:
	ds_read_b128 v[200:203], v170 offset:64
	ds_read_b128 v[204:207], v170 offset:6720
	s_waitcnt lgkmcnt(4)
	v_mfma_f32_32x32x16_bf16 v[32:47], v[184:187], v[80:83], 0
	v_mfma_f32_32x32x16_bf16 v[48:63], v[188:191], v[80:83], 0
	ds_read_b128 v[208:211], v170 offset:96
	ds_read_b128 v[212:215], v170 offset:6752
	s_waitcnt lgkmcnt(4)
	v_mfma_f32_32x32x16_bf16 v[32:47], v[192:195], v[84:87], v[32:47]
	v_mfma_f32_32x32x16_bf16 v[48:63], v[196:199], v[84:87], v[48:63]
	ds_read_b128 v[184:187], v170 offset:128
	ds_read_b128 v[188:191], v170 offset:6784
	s_waitcnt lgkmcnt(4)
	v_mfma_f32_32x32x16_bf16 v[32:47], v[200:203], v[88:91], v[32:47]
	v_mfma_f32_32x32x16_bf16 v[48:63], v[204:207], v[88:91], v[48:63]
	ds_read_b128 v[192:195], v170 offset:160
	ds_read_b128 v[196:199], v170 offset:6816
	s_waitcnt lgkmcnt(4)
	v_mfma_f32_32x32x16_bf16 v[32:47], v[208:211], v[92:95], v[32:47]
	v_mfma_f32_32x32x16_bf16 v[48:63], v[212:215], v[92:95], v[48:63]
	s_waitcnt lgkmcnt(2)
	v_mfma_f32_32x32x16_bf16 v[32:47], v[184:187], v[96:99], v[32:47]
	v_mfma_f32_32x32x16_bf16 v[48:63], v[188:191], v[96:99], v[48:63]
	s_waitcnt lgkmcnt(0)
	v_mfma_f32_32x32x16_bf16 v[32:47], v[192:195], v[100:103], v[32:47]
	v_mfma_f32_32x32x16_bf16 v[48:63], v[196:199], v[100:103], v[48:63]
	s_nop 11
	v_max3_f32 v174, v32, v33, v34
	v_max3_f32 v175, v48, v49, v50
	v_max3_f32 v174, v174, v35, v36
	v_max3_f32 v175, v175, v51, v52
	v_max3_f32 v174, v174, v37, v38
	v_max3_f32 v175, v175, v53, v54
	v_max3_f32 v174, v174, v39, v40
	v_max3_f32 v175, v175, v55, v56
	v_max3_f32 v174, v174, v41, v42
	v_max3_f32 v175, v175, v57, v58
	v_max3_f32 v174, v174, v43, v44
	v_max3_f32 v175, v175, v59, v60
	v_max3_f32 v174, v174, v45, v46
	v_max3_f32 v175, v175, v61, v62
	v_max3_f32 v174, v174, v47, v63
	v_max_f32_e32 v174, v174, v175
	v_mov_b32_e32 v175, v174
	s_nop 1
	v_permlane32_swap_b32_e32 v174, v175
	v_max_f32_e32 v174, v174, v175
	s_barrier
; #define SBAR() __builtin_amdgcn_sched_barrier(0)
; #define SLOAD(i, k0) do { sr_[i].vs = *(const bf16x8*)(Kh + (size_t)((k0) + skey) * 2048 + 64 + sc8); \
;     sr_[i].ks = *(const bf16x8*)(Kh + (size_t)((k0) + skey) * 2048 + sc8); \
;     sr_[i].ps = *(const bf16x8*)(Kp + (size_t)((k0) + pkey) * 32 + pc8); } while (0)
; #define SWRITE(bb, i) do { *(bf16x8*)(V_lds + (bb) * AT_SHMV + vst) = sr_[i].vs; \
;     *(bf16x8*)(K_lds + (bb) * AT_SHMK + kst) = sr_[i].ks; \
;     *(bf16x8*)(K_lds + (bb) * AT_SHMK + pst) = sr_[i].ps; } while (0)
; #define SWAIT() asm volatile("s_waitcnt vmcnt(3)" ::: "memory")
; __device__ __forceinline__ void at_partialSM(f32x16& p0, f32x16& p1, float& m_reg, float& alpha, bool force) {
;     ...
;   if (__builtin_expect(!force && __all(pm <= AT_THR * 1.4426950408889634f), 1)) { alpha = 1.f; }
;   else {
;     const float dlt = force ? pm : fmaxf(pm, 0.f);
;     alpha = force ? 1.f : __builtin_amdgcn_exp2f(-dlt); m_reg += dlt;
; #pragma unroll
;     for (int r = 0; r < 16; ++r) { p0[r] -= dlt; p1[r] -= dlt; }
;   }
; #pragma unroll
;   for (int r = 0; r < 16; ++r) p0[r] = __builtin_amdgcn_exp2f(p0[r]);
; }
; __device__ __forceinline__ void at_finishSM(f32x16& p0, f32x16& p1, float alpha, float& l_reg, bf16x8& pa0, bf16x8& pa1, bf16x8& pa2, bf16x8& pa3) {
; #pragma unroll
;   for (int r = 0; r < 16; ++r) p1[r] = __builtin_amdgcn_exp2f(p1[r]);
;   float ps = 0;
; #pragma unroll
;   for (int r = 0; r < 16; ++r) ps += p0[r];
; #pragma unroll
;   for (int r = 0; r < 16; ++r) ps += p1[r];
;   { auto rr = __builtin_amdgcn_permlane32_swap(__float_as_uint(ps), __float_as_uint(ps), false, false);
;     ps = __uint_as_float(rr[0]) + __uint_as_float(rr[1]); }
;   l_reg = l_reg * alpha + ps;
;     ...
;   PK4(p0, 0, pa0); PK4(p0, 8, pa1); PK4(p1, 0, pa2); PK4(p1, 8, pa3);
; __device__ void phase_attn(const Params& p, char* lds) {
;     ...
;     SLOAD(0, 0); asm volatile("s_waitcnt vmcnt(0)" ::: "memory"); SWRITE(0, 0); __syncthreads();
;     at_qkt(pA0, pA1, K_lds, qr, r32, hi, 0.f); at_partialSM(pA0, pA1, m_reg, alA, true);
;     SLOAD(1, 64); SLOAD(0, 128);
;     SWAIT(); SWRITE(1, 1); __syncthreads();
;     for (int j = 1; j + 1 < NT; j += 2) {
;       SBAR(); at_qkt(pB0, pB1, K_lds + AT_SHMK, qr, r32, hi, -m_reg);
;       at_finishSM(pA0, pA1, alA, l_reg, pa0, pa1, pa2, pa3); SBAR();
;       SLOAD(1, (j + 2) * 64); SBAR();
	v_mov_b32_e32 v172, v174
	v_sub_f32_e32 v32, v32, v174
	v_sub_f32_e32 v48, v48, v174
	v_sub_f32_e32 v33, v33, v174
	v_sub_f32_e32 v49, v49, v174
	v_sub_f32_e32 v34, v34, v174
	v_sub_f32_e32 v50, v50, v174
	v_sub_f32_e32 v35, v35, v174
	v_sub_f32_e32 v51, v51, v174
	v_sub_f32_e32 v36, v36, v174
	v_sub_f32_e32 v52, v52, v174
	v_sub_f32_e32 v37, v37, v174
	v_sub_f32_e32 v53, v53, v174
	v_sub_f32_e32 v38, v38, v174
	v_sub_f32_e32 v54, v54, v174
	v_sub_f32_e32 v39, v39, v174
	v_sub_f32_e32 v55, v55, v174
	v_sub_f32_e32 v40, v40, v174
	v_sub_f32_e32 v56, v56, v174
	v_sub_f32_e32 v41, v41, v174
	v_sub_f32_e32 v57, v57, v174
	v_sub_f32_e32 v42, v42, v174
	v_sub_f32_e32 v58, v58, v174
	v_sub_f32_e32 v43, v43, v174
	v_sub_f32_e32 v59, v59, v174
	v_sub_f32_e32 v44, v44, v174
	v_sub_f32_e32 v60, v60, v174
	v_sub_f32_e32 v45, v45, v174
	v_sub_f32_e32 v61, v61, v174
	v_sub_f32_e32 v46, v46, v174
	v_sub_f32_e32 v62, v62, v174
	v_sub_f32_e32 v47, v47, v174
	v_sub_f32_e32 v63, v63, v174
	v_sub_f32_e32 v64, 0, v174
	v_sub_f32_e32 v65, 0, v174
	v_sub_f32_e32 v66, 0, v174
	v_sub_f32_e32 v67, 0, v174
	v_sub_f32_e32 v68, 0, v174
	v_sub_f32_e32 v69, 0, v174
	v_sub_f32_e32 v70, 0, v174
	v_sub_f32_e32 v71, 0, v174
	v_sub_f32_e32 v72, 0, v174
	v_sub_f32_e32 v73, 0, v174
	v_sub_f32_e32 v74, 0, v174
	v_sub_f32_e32 v75, 0, v174
	v_sub_f32_e32 v76, 0, v174
	v_sub_f32_e32 v77, 0, v174
	v_sub_f32_e32 v78, 0, v174
	v_sub_f32_e32 v79, 0, v174
	s_waitcnt vmcnt(0)
	ds_write_b128 v167, v[120:123] offset:26624
	ds_write_b128 v169, v[132:135] offset:26624
	s_add_i32 m0, s40, 0x8000
	s_nop 0
	global_load_lds_dwordx4 v131, s[36:37]
	s_add_u32 s36, s36, 0x40000
	s_addc_u32 s37, s37, 0
	v_exp_f32_e32 v32, v32
	v_exp_f32_e32 v48, v48
	v_exp_f32_e32 v33, v33
	v_exp_f32_e32 v49, v49
	v_exp_f32_e32 v34, v34
	v_exp_f32_e32 v50, v50
	v_exp_f32_e32 v35, v35
	v_exp_f32_e32 v51, v51
	v_exp_f32_e32 v36, v36
	v_exp_f32_e32 v52, v52
	v_exp_f32_e32 v37, v37
	v_exp_f32_e32 v53, v53
	v_exp_f32_e32 v38, v38
	v_exp_f32_e32 v54, v54
	v_exp_f32_e32 v39, v39
	v_exp_f32_e32 v55, v55
	v_exp_f32_e32 v40, v40
	v_exp_f32_e32 v56, v56
	v_exp_f32_e32 v41, v41
	v_exp_f32_e32 v57, v57
	v_exp_f32_e32 v42, v42
	v_exp_f32_e32 v58, v58
	v_exp_f32_e32 v43, v43
	v_exp_f32_e32 v59, v59
	v_exp_f32_e32 v44, v44
	v_exp_f32_e32 v60, v60
	v_exp_f32_e32 v45, v45
	v_exp_f32_e32 v61, v61
	v_exp_f32_e32 v46, v46
	v_exp_f32_e32 v62, v62
	v_exp_f32_e32 v47, v47
	v_exp_f32_e32 v63, v63
	s_waitcnt lgkmcnt(0)
	global_load_dwordx4 v[120:123], v129, s[4:5]
	global_load_dwordx4 v[132:135], v130, s[6:7]
	s_add_u32 s4, s4, 0x40000
	s_addc_u32 s5, s5, 0
	s_add_u32 s6, s6, 0x1000
	s_addc_u32 s7, s7, 0
	v_add_f32_e32 v175, v32, v33
	v_add_f32_e32 v174, v48, v49
	v_add_f32_e32 v175, v175, v34
	v_add_f32_e32 v174, v174, v50
	v_add_f32_e32 v175, v175, v35
	v_add_f32_e32 v174, v174, v51
	v_add_f32_e32 v175, v175, v36
	v_add_f32_e32 v174, v174, v52
	v_add_f32_e32 v175, v175, v37
	v_add_f32_e32 v174, v174, v53
	v_add_f32_e32 v175, v175, v38
	v_add_f32_e32 v174, v174, v54
	v_add_f32_e32 v175, v175, v39
	v_add_f32_e32 v174, v174, v55
	v_add_f32_e32 v175, v175, v40
	v_add_f32_e32 v174, v174, v56
	v_add_f32_e32 v175, v175, v41
	v_add_f32_e32 v174, v174, v57
	v_add_f32_e32 v175, v175, v42
	v_add_f32_e32 v174, v174, v58
	v_add_f32_e32 v175, v175, v43
	v_add_f32_e32 v174, v174, v59
	v_add_f32_e32 v175, v175, v44
	v_add_f32_e32 v174, v174, v60
	v_add_f32_e32 v175, v175, v45
	v_add_f32_e32 v174, v174, v61
	v_add_f32_e32 v175, v175, v46
	v_add_f32_e32 v174, v174, v62
	v_add_f32_e32 v175, v175, v47
	v_add_f32_e32 v174, v174, v63
	v_add_f32_e32 v175, v175, v174
	v_add_f32_e32 v173, v173, v175
	v_cvt_pk_bf16_f32 v104, v32, v33
	v_cvt_pk_bf16_f32 v105, v34, v35
	v_cvt_pk_bf16_f32 v106, v36, v37
	v_cvt_pk_bf16_f32 v107, v38, v39
	v_cvt_pk_bf16_f32 v108, v40, v41
	v_cvt_pk_bf16_f32 v109, v42, v43
	v_cvt_pk_bf16_f32 v110, v44, v45
	v_cvt_pk_bf16_f32 v111, v46, v47
	v_cvt_pk_bf16_f32 v112, v48, v49
	v_cvt_pk_bf16_f32 v113, v50, v51
	v_cvt_pk_bf16_f32 v114, v52, v53
	v_cvt_pk_bf16_f32 v115, v54, v55
	v_cvt_pk_bf16_f32 v116, v56, v57
	v_cvt_pk_bf16_f32 v117, v58, v59
	v_cvt_pk_bf16_f32 v118, v60, v61
	v_cvt_pk_bf16_f32 v119, v62, v63
	ds_read_b128 v[184:187], v170 offset:13312
	ds_read_b128 v[188:191], v170 offset:19968
	ds_read_b128 v[192:195], v170 offset:13344
	ds_read_b128 v[196:199], v170 offset:20000
	s_barrier
	s_mov_b32 s13, 32
; #define MFMA(a, b, c) __builtin_amdgcn_mfma_f32_32x32x16_bf16((a), (b), (c), 0, 0, 0)
; #define SBAR() __builtin_amdgcn_sched_barrier(0)
; #define SWAIT() asm volatile("s_waitcnt vmcnt(3)" ::: "memory")
; __device__ __forceinline__ void at_qkt(f32x16& p0, f32x16& p1, const char* Ks, const bf16x8* qr, int r32, int hi, float negm) {
; #pragma unroll
;   for (int r = 0; r < 16; ++r) { p0[r] = negm; p1[r] = negm; }
; #pragma unroll
;   for (int d0 = 0; d0 < 6; ++d0) {
;     const bf16x8 b0 = *(const bf16x8*)(Ks + r32 * AT_KROW + d0 * 32 + hi * 16);
;     const bf16x8 b1 = *(const bf16x8*)(Ks + (32 + r32) * AT_KROW + d0 * 32 + hi * 16);
;     p0 = MFMA(b0, qr[d0], p0);
;     p1 = MFMA(b1, qr[d0], p1);
;   }
; }
; __device__ __forceinline__ int v_st(int k, int c) { const int kk = (k & ~0xC) | ((k & 4) << 1) | ((k & 8) >> 1); return ((kk >> 3) * 4 + (c >> 5)) * 512 + ((kk & 7) * 32 + (c & 31)) * 2; }
; __device__ __forceinline__ int v_rd_base(int lane) { return ((lane & 3) << 3) | (((lane >> 2) & 3) << 6) | (((lane >> 4) & 1) << 5) | (((lane >> 5) & 1) << 8); }
; template <int OFF> __device__ __forceinline__ s16x4 tr_read(int vb) {
;   s16x4 r; asm volatile("ds_read_b64_tr_b16 %0, %1 offset:%2" : "=&v"(r) : "v"(vb), "i"(OFF) : "memory"); return r;
; }
; template <int D0> __device__ __forceinline__ void pv_one(f32x16& od, int vb, bf16x8 pa0, bf16x8 pa1, bf16x8 pa2, bf16x8 pa3) {
;   const s16x4 l0 = tr_read<v_rd_off(D0, 0, 0)>(vb), h0 = tr_read<v_rd_off(D0, 0, 1)>(vb), l1 = tr_read<v_rd_off(D0, 1, 0)>(vb), h1 = tr_read<v_rd_off(D0, 1, 1)>(vb);
;   const s16x4 l2 = tr_read<v_rd_off(D0, 2, 0)>(vb), h2 = tr_read<v_rd_off(D0, 2, 1)>(vb), l3 = tr_read<v_rd_off(D0, 3, 0)>(vb), h3 = tr_read<v_rd_off(D0, 3, 1)>(vb);
;   asm volatile("s_waitcnt lgkmcnt(0)" ::: "memory"); SBAR();
;     ...
;   od = MFMA(pa0, PK(l0, h0), od);
;   od = MFMA(pa1, PK(l1, h1), od);
;   od = MFMA(pa2, PK(l2, h2), od);
;   od = MFMA(pa3, PK(l3, h3), od);
;     ...
; }
; __device__ void phase_attn(const Params& p, char* lds) {
;     ...
;     for (int j = 1; j + 1 < NT; j += 2) {
;       SBAR(); at_qkt(pB0, pB1, K_lds + AT_SHMK, qr, r32, hi, -m_reg);
;       at_finishSM(pA0, pA1, alA, l_reg, pa0, pa1, pa2, pa3); SBAR();
;       SLOAD(1, (j + 2) * 64); SBAR();
;       pv_d0(o, vb0, pa0, pa1, pa2, pa3); at_partialSM(pB0, pB1, m_reg, alB, false);
;       __syncthreads(); SWAIT(); SWRITE(0, 0);
;       RESC(alB); __syncthreads();
.Lat_loop:
	ds_read_b128 v[200:203], v170 offset:13376
	ds_read_b128 v[204:207], v170 offset:20032
	s_waitcnt lgkmcnt(4)
	v_mfma_f32_32x32x16_bf16 v[32:47], v[184:187], v[80:83], v[64:79]
	v_mfma_f32_32x32x16_bf16 v[48:63], v[188:191], v[80:83], v[64:79]
	ds_read_b128 v[208:211], v170 offset:13408
	ds_read_b128 v[212:215], v170 offset:20064
	s_waitcnt lgkmcnt(4)
	v_mfma_f32_32x32x16_bf16 v[32:47], v[192:195], v[84:87], v[32:47]
	v_mfma_f32_32x32x16_bf16 v[48:63], v[196:199], v[84:87], v[48:63]
	ds_read_b128 v[184:187], v170 offset:13440
	ds_read_b128 v[188:191], v170 offset:20096
	s_waitcnt lgkmcnt(4)
	v_mfma_f32_32x32x16_bf16 v[32:47], v[200:203], v[88:91], v[32:47]
	v_mfma_f32_32x32x16_bf16 v[48:63], v[204:207], v[88:91], v[48:63]
	ds_read_b128 v[192:195], v170 offset:13472
	ds_read_b128 v[196:199], v170 offset:20128
	s_waitcnt lgkmcnt(4)
	v_mfma_f32_32x32x16_bf16 v[32:47], v[208:211], v[92:95], v[32:47]
	v_mfma_f32_32x32x16_bf16 v[48:63], v[212:215], v[92:95], v[48:63]
	ds_read_b64_tr_b16 v[148:149], v171 offset:0
	ds_read_b64_tr_b16 v[150:151], v171 offset:2048
	ds_read_b64_tr_b16 v[152:153], v171 offset:4096
	ds_read_b64_tr_b16 v[154:155], v171 offset:6144
	s_waitcnt lgkmcnt(6)
	v_mfma_f32_32x32x16_bf16 v[32:47], v[184:187], v[96:99], v[32:47]
	v_mfma_f32_32x32x16_bf16 v[48:63], v[188:191], v[96:99], v[48:63]
	ds_read_b64_tr_b16 v[156:157], v171 offset:8192
	ds_read_b64_tr_b16 v[158:159], v171 offset:10240
	ds_read_b64_tr_b16 v[216:217], v171 offset:12288
	ds_read_b64_tr_b16 v[218:219], v171 offset:14336
	s_waitcnt lgkmcnt(8)
	v_mfma_f32_32x32x16_bf16 v[32:47], v[192:195], v[100:103], v[32:47]
	v_mfma_f32_32x32x16_bf16 v[48:63], v[196:199], v[100:103], v[48:63]
	ds_read_b64_tr_b16 v[220:221], v171 offset:512
	ds_read_b64_tr_b16 v[222:223], v171 offset:2560
	ds_read_b64_tr_b16 v[224:225], v171 offset:4608
	ds_read_b64_tr_b16 v[226:227], v171 offset:6656
	s_waitcnt lgkmcnt(10)
	v_mfma_f32_32x32x16_bf16 v[0:15], v[104:107], v[148:151], v[0:15]
	s_waitcnt lgkmcnt(8)
	v_mfma_f32_32x32x16_bf16 v[0:15], v[108:111], v[152:155], v[0:15]
	ds_read_b64_tr_b16 v[236:237], v171 offset:8704
	ds_read_b64_tr_b16 v[238:239], v171 offset:10752
	ds_read_b64_tr_b16 v[240:241], v171 offset:12800
	ds_read_b64_tr_b16 v[242:243], v171 offset:14848
	s_waitcnt lgkmcnt(10)
	v_mfma_f32_32x32x16_bf16 v[0:15], v[112:115], v[156:159], v[0:15]
	s_waitcnt lgkmcnt(8)
	v_mfma_f32_32x32x16_bf16 v[0:15], v[116:119], v[216:219], v[0:15]
	s_waitcnt lgkmcnt(6)
	v_mfma_f32_32x32x16_bf16 v[16:31], v[104:107], v[220:223], v[16:31]
	s_waitcnt lgkmcnt(4)
	v_mfma_f32_32x32x16_bf16 v[16:31], v[108:111], v[224:227], v[16:31]
	s_waitcnt lgkmcnt(2)
	v_mfma_f32_32x32x16_bf16 v[16:31], v[112:115], v[236:239], v[16:31]
	s_waitcnt lgkmcnt(0)
	v_mfma_f32_32x32x16_bf16 v[16:31], v[116:119], v[240:243], v[16:31]
	s_barrier
	s_waitcnt vmcnt(0)
	ds_write_b128 v167, v[120:123] offset:39936
	ds_write_b128 v169, v[132:135] offset:39936
	s_add_i32 m0, s40, 0xc000
	s_nop 0
	global_load_lds_dwordx4 v131, s[36:37]
	s_add_u32 s36, s36, 0x40000
	s_addc_u32 s37, s37, 0
	v_exp_f32_e32 v32, v32
	v_exp_f32_e32 v48, v48
	v_exp_f32_e32 v33, v33
	v_exp_f32_e32 v49, v49
	v_exp_f32_e32 v34, v34
	v_exp_f32_e32 v50, v50
	v_exp_f32_e32 v35, v35
	v_exp_f32_e32 v51, v51
	v_exp_f32_e32 v36, v36
	v_exp_f32_e32 v52, v52
	v_exp_f32_e32 v37, v37
	v_exp_f32_e32 v53, v53
	v_exp_f32_e32 v38, v38
	v_exp_f32_e32 v54, v54
	v_exp_f32_e32 v39, v39
	v_exp_f32_e32 v55, v55
	v_exp_f32_e32 v40, v40
	v_exp_f32_e32 v56, v56
	v_exp_f32_e32 v41, v41
	v_exp_f32_e32 v57, v57
	v_exp_f32_e32 v42, v42
	v_exp_f32_e32 v58, v58
	v_exp_f32_e32 v43, v43
	v_exp_f32_e32 v59, v59
	v_exp_f32_e32 v44, v44
	v_exp_f32_e32 v60, v60
	v_exp_f32_e32 v45, v45
	v_exp_f32_e32 v61, v61
	v_exp_f32_e32 v46, v46
	v_exp_f32_e32 v62, v62
	v_exp_f32_e32 v47, v47
	v_exp_f32_e32 v63, v63
	s_waitcnt lgkmcnt(0)
	global_load_dwordx4 v[120:123], v129, s[4:5]
	global_load_dwordx4 v[132:135], v130, s[6:7]
	s_add_u32 s4, s4, 0x40000
	s_addc_u32 s5, s5, 0
	s_add_u32 s6, s6, 0x1000
	s_addc_u32 s7, s7, 0
	v_add_f32_e32 v175, v32, v33
	v_add_f32_e32 v174, v48, v49
	v_add_f32_e32 v175, v175, v34
	v_add_f32_e32 v174, v174, v50
	v_add_f32_e32 v175, v175, v35
	v_add_f32_e32 v174, v174, v51
	v_add_f32_e32 v175, v175, v36
	v_add_f32_e32 v174, v174, v52
	v_add_f32_e32 v175, v175, v37
	v_add_f32_e32 v174, v174, v53
	v_add_f32_e32 v175, v175, v38
	v_add_f32_e32 v174, v174, v54
	v_add_f32_e32 v175, v175, v39
	v_add_f32_e32 v174, v174, v55
	v_add_f32_e32 v175, v175, v40
	v_add_f32_e32 v174, v174, v56
	v_add_f32_e32 v175, v175, v41
	v_add_f32_e32 v174, v174, v57
	v_add_f32_e32 v175, v175, v42
	v_add_f32_e32 v174, v174, v58
	v_add_f32_e32 v175, v175, v43
	v_add_f32_e32 v174, v174, v59
	v_add_f32_e32 v175, v175, v44
	v_add_f32_e32 v174, v174, v60
	v_add_f32_e32 v175, v175, v45
	v_add_f32_e32 v174, v174, v61
	v_add_f32_e32 v175, v175, v46
	v_add_f32_e32 v174, v174, v62
	v_add_f32_e32 v175, v175, v47
	v_add_f32_e32 v174, v174, v63
	v_add_f32_e32 v175, v175, v174
	v_cmp_ge_f32_e32 vcc, s23, v175
	s_cmp_eq_u64 vcc, exec
	s_cbranch_scc0 .Lat_rare0
; #define MFMA(a, b, c) __builtin_amdgcn_mfma_f32_32x32x16_bf16((a), (b), (c), 0, 0, 0)
; #define SBAR() __builtin_amdgcn_sched_barrier(0)
; #define SWAIT() asm volatile("s_waitcnt vmcnt(3)" ::: "memory")
; __device__ __forceinline__ void at_qkt(f32x16& p0, f32x16& p1, const char* Ks, const bf16x8* qr, int r32, int hi, float negm) {
; #pragma unroll
;   for (int r = 0; r < 16; ++r) { p0[r] = negm; p1[r] = negm; }
; #pragma unroll
;   for (int d0 = 0; d0 < 6; ++d0) {
;     const bf16x8 b0 = *(const bf16x8*)(Ks + r32 * AT_KROW + d0 * 32 + hi * 16);
;     const bf16x8 b1 = *(const bf16x8*)(Ks + (32 + r32) * AT_KROW + d0 * 32 + hi * 16);
;     p0 = MFMA(b0, qr[d0], p0);
;     p1 = MFMA(b1, qr[d0], p1);
;   }
; }
; __device__ __forceinline__ int v_st(int k, int c) { const int kk = (k & ~0xC) | ((k & 4) << 1) | ((k & 8) >> 1); return ((kk >> 3) * 4 + (c >> 5)) * 512 + ((kk & 7) * 32 + (c & 31)) * 2; }
; __device__ __forceinline__ int v_rd_base(int lane) { return ((lane & 3) << 3) | (((lane >> 2) & 3) << 6) | (((lane >> 4) & 1) << 5) | (((lane >> 5) & 1) << 8); }
; template <int OFF> __device__ __forceinline__ s16x4 tr_read(int vb) {
;   s16x4 r; asm volatile("ds_read_b64_tr_b16 %0, %1 offset:%2" : "=&v"(r) : "v"(vb), "i"(OFF) : "memory"); return r;
; }
; template <int D0> __device__ __forceinline__ void pv_one(f32x16& od, int vb, bf16x8 pa0, bf16x8 pa1, bf16x8 pa2, bf16x8 pa3) {
;   const s16x4 l0 = tr_read<v_rd_off(D0, 0, 0)>(vb), h0 = tr_read<v_rd_off(D0, 0, 1)>(vb), l1 = tr_read<v_rd_off(D0, 1, 0)>(vb), h1 = tr_read<v_rd_off(D0, 1, 1)>(vb);
;   const s16x4 l2 = tr_read<v_rd_off(D0, 2, 0)>(vb), h2 = tr_read<v_rd_off(D0, 2, 1)>(vb), l3 = tr_read<v_rd_off(D0, 3, 0)>(vb), h3 = tr_read<v_rd_off(D0, 3, 1)>(vb);
;   asm volatile("s_waitcnt lgkmcnt(0)" ::: "memory"); SBAR();
;     ...
;   od = MFMA(pa0, PK(l0, h0), od);
;   od = MFMA(pa1, PK(l1, h1), od);
;   od = MFMA(pa2, PK(l2, h2), od);
;   od = MFMA(pa3, PK(l3, h3), od);
;     ...
; }
; __device__ void phase_attn(const Params& p, char* lds) {
;     ...
;       SBAR(); at_qkt(pA0, pA1, K_lds, qr, r32, hi, -m_reg);
;       at_finishSM(pB0, pB1, alB, l_reg, pa0, pa1, pa2, pa3); SBAR();
;       if (j + 3 < NT) SLOAD(0, (j + 3) * 64); SBAR();
;       pv_d0(o, vb0 + AT_SHMV, pa0, pa1, pa2, pa3); at_partialSM(pA0, pA1, m_reg, alA, false);
;       __syncthreads(); SWAIT(); SWRITE(1, 1);
;       RESC(alA); __syncthreads();
.Lat_rare0_back:
	v_add_f32_e32 v173, v173, v175
	v_cvt_pk_bf16_f32 v104, v32, v33
	v_cvt_pk_bf16_f32 v105, v34, v35
	v_cvt_pk_bf16_f32 v106, v36, v37
	v_cvt_pk_bf16_f32 v107, v38, v39
	v_cvt_pk_bf16_f32 v108, v40, v41
	v_cvt_pk_bf16_f32 v109, v42, v43
	v_cvt_pk_bf16_f32 v110, v44, v45
	v_cvt_pk_bf16_f32 v111, v46, v47
	v_cvt_pk_bf16_f32 v112, v48, v49
	v_cvt_pk_bf16_f32 v113, v50, v51
	v_cvt_pk_bf16_f32 v114, v52, v53
	v_cvt_pk_bf16_f32 v115, v54, v55
	v_cvt_pk_bf16_f32 v116, v56, v57
	v_cvt_pk_bf16_f32 v117, v58, v59
	v_cvt_pk_bf16_f32 v118, v60, v61
	v_cvt_pk_bf16_f32 v119, v62, v63
	ds_read_b128 v[184:187], v170 offset:26624
	ds_read_b128 v[188:191], v170 offset:33280
	ds_read_b128 v[192:195], v170 offset:26656
	ds_read_b128 v[196:199], v170 offset:33312
	s_barrier
	ds_read_b128 v[200:203], v170 offset:26688
	ds_read_b128 v[204:207], v170 offset:33344
	s_waitcnt lgkmcnt(4)
	v_mfma_f32_32x32x16_bf16 v[32:47], v[184:187], v[80:83], v[64:79]
	v_mfma_f32_32x32x16_bf16 v[48:63], v[188:191], v[80:83], v[64:79]
	ds_read_b128 v[208:211], v170 offset:26720
	ds_read_b128 v[212:215], v170 offset:33376
	s_waitcnt lgkmcnt(4)
	v_mfma_f32_32x32x16_bf16 v[32:47], v[192:195], v[84:87], v[32:47]
	v_mfma_f32_32x32x16_bf16 v[48:63], v[196:199], v[84:87], v[48:63]
	ds_read_b128 v[184:187], v170 offset:26752
	ds_read_b128 v[188:191], v170 offset:33408
	s_waitcnt lgkmcnt(4)
	v_mfma_f32_32x32x16_bf16 v[32:47], v[200:203], v[88:91], v[32:47]
	v_mfma_f32_32x32x16_bf16 v[48:63], v[204:207], v[88:91], v[48:63]
	ds_read_b128 v[192:195], v170 offset:26784
	ds_read_b128 v[196:199], v170 offset:33440
	s_waitcnt lgkmcnt(4)
	v_mfma_f32_32x32x16_bf16 v[32:47], v[208:211], v[92:95], v[32:47]
	v_mfma_f32_32x32x16_bf16 v[48:63], v[212:215], v[92:95], v[48:63]
	ds_read_b64_tr_b16 v[148:149], v171 offset:16384
	ds_read_b64_tr_b16 v[150:151], v171 offset:18432
	ds_read_b64_tr_b16 v[152:153], v171 offset:20480
	ds_read_b64_tr_b16 v[154:155], v171 offset:22528
	s_waitcnt lgkmcnt(6)
	v_mfma_f32_32x32x16_bf16 v[32:47], v[184:187], v[96:99], v[32:47]
	v_mfma_f32_32x32x16_bf16 v[48:63], v[188:191], v[96:99], v[48:63]
	ds_read_b64_tr_b16 v[156:157], v171 offset:24576
	ds_read_b64_tr_b16 v[158:159], v171 offset:26624
	ds_read_b64_tr_b16 v[216:217], v171 offset:28672
	ds_read_b64_tr_b16 v[218:219], v171 offset:30720
	s_waitcnt lgkmcnt(8)
	v_mfma_f32_32x32x16_bf16 v[32:47], v[192:195], v[100:103], v[32:47]
	v_mfma_f32_32x32x16_bf16 v[48:63], v[196:199], v[100:103], v[48:63]
	ds_read_b64_tr_b16 v[220:221], v171 offset:16896
	ds_read_b64_tr_b16 v[222:223], v171 offset:18944
	ds_read_b64_tr_b16 v[224:225], v171 offset:20992
	ds_read_b64_tr_b16 v[226:227], v171 offset:23040
	s_waitcnt lgkmcnt(10)
	v_mfma_f32_32x32x16_bf16 v[0:15], v[104:107], v[148:151], v[0:15]
	s_waitcnt lgkmcnt(8)
	v_mfma_f32_32x32x16_bf16 v[0:15], v[108:111], v[152:155], v[0:15]
	ds_read_b64_tr_b16 v[236:237], v171 offset:25088
	ds_read_b64_tr_b16 v[238:239], v171 offset:27136
	ds_read_b64_tr_b16 v[240:241], v171 offset:29184
	ds_read_b64_tr_b16 v[242:243], v171 offset:31232
	s_waitcnt lgkmcnt(10)
	v_mfma_f32_32x32x16_bf16 v[0:15], v[112:115], v[156:159], v[0:15]
	s_waitcnt lgkmcnt(8)
	v_mfma_f32_32x32x16_bf16 v[0:15], v[116:119], v[216:219], v[0:15]
	s_waitcnt lgkmcnt(6)
	v_mfma_f32_32x32x16_bf16 v[16:31], v[104:107], v[220:223], v[16:31]
	s_waitcnt lgkmcnt(4)
	v_mfma_f32_32x32x16_bf16 v[16:31], v[108:111], v[224:227], v[16:31]
	s_waitcnt lgkmcnt(2)
	v_mfma_f32_32x32x16_bf16 v[16:31], v[112:115], v[236:239], v[16:31]
	s_waitcnt lgkmcnt(0)
	v_mfma_f32_32x32x16_bf16 v[16:31], v[116:119], v[240:243], v[16:31]
	s_barrier
	s_waitcnt vmcnt(0)
	ds_write_b128 v167, v[120:123] offset:0
	ds_write_b128 v169, v[132:135] offset:0
	s_add_i32 m0, s40, 0x0
	s_nop 0
	global_load_lds_dwordx4 v131, s[36:37]
	s_add_u32 s36, s36, 0x40000
	s_addc_u32 s37, s37, 0
	v_exp_f32_e32 v32, v32
	v_exp_f32_e32 v48, v48
	v_exp_f32_e32 v33, v33
	v_exp_f32_e32 v49, v49
	v_exp_f32_e32 v34, v34
	v_exp_f32_e32 v50, v50
	v_exp_f32_e32 v35, v35
	v_exp_f32_e32 v51, v51
	v_exp_f32_e32 v36, v36
	v_exp_f32_e32 v52, v52
	v_exp_f32_e32 v37, v37
	v_exp_f32_e32 v53, v53
	v_exp_f32_e32 v38, v38
	v_exp_f32_e32 v54, v54
	v_exp_f32_e32 v39, v39
	v_exp_f32_e32 v55, v55
	v_exp_f32_e32 v40, v40
	v_exp_f32_e32 v56, v56
	v_exp_f32_e32 v41, v41
	v_exp_f32_e32 v57, v57
	v_exp_f32_e32 v42, v42
	v_exp_f32_e32 v58, v58
	v_exp_f32_e32 v43, v43
	v_exp_f32_e32 v59, v59
	v_exp_f32_e32 v44, v44
	v_exp_f32_e32 v60, v60
	v_exp_f32_e32 v45, v45
	v_exp_f32_e32 v61, v61
	v_exp_f32_e32 v46, v46
	v_exp_f32_e32 v62, v62
	v_exp_f32_e32 v47, v47
	v_exp_f32_e32 v63, v63
	s_waitcnt lgkmcnt(0)
	global_load_dwordx4 v[120:123], v129, s[4:5]
	global_load_dwordx4 v[132:135], v130, s[6:7]
	s_add_u32 s4, s4, 0x40000
	s_addc_u32 s5, s5, 0
	s_add_u32 s6, s6, 0x1000
	s_addc_u32 s7, s7, 0
	v_add_f32_e32 v175, v32, v33
	v_add_f32_e32 v174, v48, v49
	v_add_f32_e32 v175, v175, v34
	v_add_f32_e32 v174, v174, v50
	v_add_f32_e32 v175, v175, v35
	v_add_f32_e32 v174, v174, v51
	v_add_f32_e32 v175, v175, v36
	v_add_f32_e32 v174, v174, v52
	v_add_f32_e32 v175, v175, v37
	v_add_f32_e32 v174, v174, v53
	v_add_f32_e32 v175, v175, v38
	v_add_f32_e32 v174, v174, v54
	v_add_f32_e32 v175, v175, v39
	v_add_f32_e32 v174, v174, v55
	v_add_f32_e32 v175, v175, v40
	v_add_f32_e32 v174, v174, v56
	v_add_f32_e32 v175, v175, v41
	v_add_f32_e32 v174, v174, v57
	v_add_f32_e32 v175, v175, v42
	v_add_f32_e32 v174, v174, v58
	v_add_f32_e32 v175, v175, v43
	v_add_f32_e32 v174, v174, v59
	v_add_f32_e32 v175, v175, v44
	v_add_f32_e32 v174, v174, v60
	v_add_f32_e32 v175, v175, v45
	v_add_f32_e32 v174, v174, v61
	v_add_f32_e32 v175, v175, v46
	v_add_f32_e32 v174, v174, v62
	v_add_f32_e32 v175, v175, v47
	v_add_f32_e32 v174, v174, v63
	v_add_f32_e32 v175, v175, v174
	v_cmp_ge_f32_e32 vcc, s23, v175
	s_cmp_eq_u64 vcc, exec
	s_cbranch_scc0 .Lat_rare1
; #define MFMA(a, b, c) __builtin_amdgcn_mfma_f32_32x32x16_bf16((a), (b), (c), 0, 0, 0)
; #define SBAR() __builtin_amdgcn_sched_barrier(0)
; #define SWAIT() asm volatile("s_waitcnt vmcnt(3)" ::: "memory")
; __device__ __forceinline__ void at_qkt(f32x16& p0, f32x16& p1, const char* Ks, const bf16x8* qr, int r32, int hi, float negm) {
; #pragma unroll
;   for (int r = 0; r < 16; ++r) { p0[r] = negm; p1[r] = negm; }
; #pragma unroll
;   for (int d0 = 0; d0 < 6; ++d0) {
;     const bf16x8 b0 = *(const bf16x8*)(Ks + r32 * AT_KROW + d0 * 32 + hi * 16);
;     const bf16x8 b1 = *(const bf16x8*)(Ks + (32 + r32) * AT_KROW + d0 * 32 + hi * 16);
;     p0 = MFMA(b0, qr[d0], p0);
;     p1 = MFMA(b1, qr[d0], p1);
;   }
; }
; __device__ __forceinline__ int v_st(int k, int c) { const int kk = (k & ~0xC) | ((k & 4) << 1) | ((k & 8) >> 1); return ((kk >> 3) * 4 + (c >> 5)) * 512 + ((kk & 7) * 32 + (c & 31)) * 2; }
; __device__ __forceinline__ int v_rd_base(int lane) { return ((lane & 3) << 3) | (((lane >> 2) & 3) << 6) | (((lane >> 4) & 1) << 5) | (((lane >> 5) & 1) << 8); }
; template <int OFF> __device__ __forceinline__ s16x4 tr_read(int vb) {
;   s16x4 r; asm volatile("ds_read_b64_tr_b16 %0, %1 offset:%2" : "=&v"(r) : "v"(vb), "i"(OFF) : "memory"); return r;
; }
; template <int D0> __device__ __forceinline__ void pv_one(f32x16& od, int vb, bf16x8 pa0, bf16x8 pa1, bf16x8 pa2, bf16x8 pa3) {
;   const s16x4 l0 = tr_read<v_rd_off(D0, 0, 0)>(vb), h0 = tr_read<v_rd_off(D0, 0, 1)>(vb), l1 = tr_read<v_rd_off(D0, 1, 0)>(vb), h1 = tr_read<v_rd_off(D0, 1, 1)>(vb);
;   const s16x4 l2 = tr_read<v_rd_off(D0, 2, 0)>(vb), h2 = tr_read<v_rd_off(D0, 2, 1)>(vb), l3 = tr_read<v_rd_off(D0, 3, 0)>(vb), h3 = tr_read<v_rd_off(D0, 3, 1)>(vb);
;   asm volatile("s_waitcnt lgkmcnt(0)" ::: "memory"); SBAR();
;     ...
;   od = MFMA(pa0, PK(l0, h0), od);
;   od = MFMA(pa1, PK(l1, h1), od);
;   od = MFMA(pa2, PK(l2, h2), od);
;   od = MFMA(pa3, PK(l3, h3), od);
;     ...
; }
; __device__ void phase_attn(const Params& p, char* lds) {
;     ...
;     for (int j = 1; j + 1 < NT; j += 2) {
;       SBAR(); at_qkt(pB0, pB1, K_lds + AT_SHMK, qr, r32, hi, -m_reg);
;       at_finishSM(pA0, pA1, alA, l_reg, pa0, pa1, pa2, pa3); SBAR();
;       SLOAD(1, (j + 2) * 64); SBAR();
;       pv_d0(o, vb0, pa0, pa1, pa2, pa3); at_partialSM(pB0, pB1, m_reg, alB, false);
;       __syncthreads(); SWAIT(); SWRITE(0, 0);
;       RESC(alB); __syncthreads();
.Lat_rare1_back:
	v_add_f32_e32 v173, v173, v175
	v_cvt_pk_bf16_f32 v104, v32, v33
	v_cvt_pk_bf16_f32 v105, v34, v35
	v_cvt_pk_bf16_f32 v106, v36, v37
	v_cvt_pk_bf16_f32 v107, v38, v39
	v_cvt_pk_bf16_f32 v108, v40, v41
	v_cvt_pk_bf16_f32 v109, v42, v43
	v_cvt_pk_bf16_f32 v110, v44, v45
	v_cvt_pk_bf16_f32 v111, v46, v47
	v_cvt_pk_bf16_f32 v112, v48, v49
	v_cvt_pk_bf16_f32 v113, v50, v51
	v_cvt_pk_bf16_f32 v114, v52, v53
	v_cvt_pk_bf16_f32 v115, v54, v55
	v_cvt_pk_bf16_f32 v116, v56, v57
	v_cvt_pk_bf16_f32 v117, v58, v59
	v_cvt_pk_bf16_f32 v118, v60, v61
	v_cvt_pk_bf16_f32 v119, v62, v63
	ds_read_b128 v[184:187], v170 offset:39936
	ds_read_b128 v[188:191], v170 offset:46592
	ds_read_b128 v[192:195], v170 offset:39968
	ds_read_b128 v[196:199], v170 offset:46624
	s_barrier
	ds_read_b128 v[200:203], v170 offset:40000
	ds_read_b128 v[204:207], v170 offset:46656
	s_waitcnt lgkmcnt(4)
	v_mfma_f32_32x32x16_bf16 v[32:47], v[184:187], v[80:83], v[64:79]
	v_mfma_f32_32x32x16_bf16 v[48:63], v[188:191], v[80:83], v[64:79]
	ds_read_b128 v[208:211], v170 offset:40032
	ds_read_b128 v[212:215], v170 offset:46688
	s_waitcnt lgkmcnt(4)
	v_mfma_f32_32x32x16_bf16 v[32:47], v[192:195], v[84:87], v[32:47]
	v_mfma_f32_32x32x16_bf16 v[48:63], v[196:199], v[84:87], v[48:63]
	ds_read_b128 v[184:187], v170 offset:40064
	ds_read_b128 v[188:191], v170 offset:46720
	s_waitcnt lgkmcnt(4)
	v_mfma_f32_32x32x16_bf16 v[32:47], v[200:203], v[88:91], v[32:47]
	v_mfma_f32_32x32x16_bf16 v[48:63], v[204:207], v[88:91], v[48:63]
	ds_read_b128 v[192:195], v170 offset:40096
	ds_read_b128 v[196:199], v170 offset:46752
	s_waitcnt lgkmcnt(4)
	v_mfma_f32_32x32x16_bf16 v[32:47], v[208:211], v[92:95], v[32:47]
	v_mfma_f32_32x32x16_bf16 v[48:63], v[212:215], v[92:95], v[48:63]
	ds_read_b64_tr_b16 v[148:149], v171 offset:32768
	ds_read_b64_tr_b16 v[150:151], v171 offset:34816
	ds_read_b64_tr_b16 v[152:153], v171 offset:36864
	ds_read_b64_tr_b16 v[154:155], v171 offset:38912
	s_waitcnt lgkmcnt(6)
	v_mfma_f32_32x32x16_bf16 v[32:47], v[184:187], v[96:99], v[32:47]
	v_mfma_f32_32x32x16_bf16 v[48:63], v[188:191], v[96:99], v[48:63]
	ds_read_b64_tr_b16 v[156:157], v171 offset:40960
	ds_read_b64_tr_b16 v[158:159], v171 offset:43008
	ds_read_b64_tr_b16 v[216:217], v171 offset:45056
	ds_read_b64_tr_b16 v[218:219], v171 offset:47104
	s_waitcnt lgkmcnt(8)
	v_mfma_f32_32x32x16_bf16 v[32:47], v[192:195], v[100:103], v[32:47]
	v_mfma_f32_32x32x16_bf16 v[48:63], v[196:199], v[100:103], v[48:63]
	ds_read_b64_tr_b16 v[220:221], v171 offset:33280
	ds_read_b64_tr_b16 v[222:223], v171 offset:35328
	ds_read_b64_tr_b16 v[224:225], v171 offset:37376
	ds_read_b64_tr_b16 v[226:227], v171 offset:39424
	s_waitcnt lgkmcnt(10)
	v_mfma_f32_32x32x16_bf16 v[0:15], v[104:107], v[148:151], v[0:15]
	s_waitcnt lgkmcnt(8)
	v_mfma_f32_32x32x16_bf16 v[0:15], v[108:111], v[152:155], v[0:15]
	ds_read_b64_tr_b16 v[236:237], v171 offset:41472
	ds_read_b64_tr_b16 v[238:239], v171 offset:43520
	ds_read_b64_tr_b16 v[240:241], v171 offset:45568
	ds_read_b64_tr_b16 v[242:243], v171 offset:47616
	s_waitcnt lgkmcnt(10)
	v_mfma_f32_32x32x16_bf16 v[0:15], v[112:115], v[156:159], v[0:15]
	s_waitcnt lgkmcnt(8)
	v_mfma_f32_32x32x16_bf16 v[0:15], v[116:119], v[216:219], v[0:15]
	s_waitcnt lgkmcnt(6)
	v_mfma_f32_32x32x16_bf16 v[16:31], v[104:107], v[220:223], v[16:31]
	s_waitcnt lgkmcnt(4)
	v_mfma_f32_32x32x16_bf16 v[16:31], v[108:111], v[224:227], v[16:31]
	s_waitcnt lgkmcnt(2)
	v_mfma_f32_32x32x16_bf16 v[16:31], v[112:115], v[236:239], v[16:31]
	s_waitcnt lgkmcnt(0)
	v_mfma_f32_32x32x16_bf16 v[16:31], v[116:119], v[240:243], v[16:31]
	s_barrier
	s_waitcnt vmcnt(0)
	ds_write_b128 v167, v[120:123] offset:13312
	ds_write_b128 v169, v[132:135] offset:13312
	s_add_i32 m0, s40, 0x4000
	s_nop 0
	global_load_lds_dwordx4 v131, s[36:37]
	s_add_u32 s36, s36, 0x40000
	s_addc_u32 s37, s37, 0
	v_exp_f32_e32 v32, v32
	v_exp_f32_e32 v48, v48
	v_exp_f32_e32 v33, v33
	v_exp_f32_e32 v49, v49
	v_exp_f32_e32 v34, v34
	v_exp_f32_e32 v50, v50
	v_exp_f32_e32 v35, v35
	v_exp_f32_e32 v51, v51
	v_exp_f32_e32 v36, v36
	v_exp_f32_e32 v52, v52
	v_exp_f32_e32 v37, v37
	v_exp_f32_e32 v53, v53
	v_exp_f32_e32 v38, v38
	v_exp_f32_e32 v54, v54
	v_exp_f32_e32 v39, v39
	v_exp_f32_e32 v55, v55
	v_exp_f32_e32 v40, v40
	v_exp_f32_e32 v56, v56
	v_exp_f32_e32 v41, v41
	v_exp_f32_e32 v57, v57
	v_exp_f32_e32 v42, v42
	v_exp_f32_e32 v58, v58
	v_exp_f32_e32 v43, v43
	v_exp_f32_e32 v59, v59
	v_exp_f32_e32 v44, v44
	v_exp_f32_e32 v60, v60
	v_exp_f32_e32 v45, v45
	v_exp_f32_e32 v61, v61
	v_exp_f32_e32 v46, v46
	v_exp_f32_e32 v62, v62
	v_exp_f32_e32 v47, v47
	v_exp_f32_e32 v63, v63
	s_waitcnt lgkmcnt(0)
	global_load_dwordx4 v[120:123], v129, s[4:5]
	global_load_dwordx4 v[132:135], v130, s[6:7]
	s_add_u32 s4, s4, 0x40000
	s_addc_u32 s5, s5, 0
	s_add_u32 s6, s6, 0x1000
	s_addc_u32 s7, s7, 0
	v_add_f32_e32 v175, v32, v33
	v_add_f32_e32 v174, v48, v49
	v_add_f32_e32 v175, v175, v34
	v_add_f32_e32 v174, v174, v50
	v_add_f32_e32 v175, v175, v35
	v_add_f32_e32 v174, v174, v51
	v_add_f32_e32 v175, v175, v36
	v_add_f32_e32 v174, v174, v52
	v_add_f32_e32 v175, v175, v37
	v_add_f32_e32 v174, v174, v53
	v_add_f32_e32 v175, v175, v38
	v_add_f32_e32 v174, v174, v54
	v_add_f32_e32 v175, v175, v39
	v_add_f32_e32 v174, v174, v55
	v_add_f32_e32 v175, v175, v40
	v_add_f32_e32 v174, v174, v56
	v_add_f32_e32 v175, v175, v41
	v_add_f32_e32 v174, v174, v57
	v_add_f32_e32 v175, v175, v42
	v_add_f32_e32 v174, v174, v58
	v_add_f32_e32 v175, v175, v43
	v_add_f32_e32 v174, v174, v59
	v_add_f32_e32 v175, v175, v44
	v_add_f32_e32 v174, v174, v60
	v_add_f32_e32 v175, v175, v45
	v_add_f32_e32 v174, v174, v61
	v_add_f32_e32 v175, v175, v46
	v_add_f32_e32 v174, v174, v62
	v_add_f32_e32 v175, v175, v47
	v_add_f32_e32 v174, v174, v63
	v_add_f32_e32 v175, v175, v174
	v_cmp_ge_f32_e32 vcc, s23, v175
	s_cmp_eq_u64 vcc, exec
	s_cbranch_scc0 .Lat_rare2
; #define MFMA(a, b, c) __builtin_amdgcn_mfma_f32_32x32x16_bf16((a), (b), (c), 0, 0, 0)
; #define SBAR() __builtin_amdgcn_sched_barrier(0)
; #define SWAIT() asm volatile("s_waitcnt vmcnt(3)" ::: "memory")
; __device__ __forceinline__ void at_qkt(f32x16& p0, f32x16& p1, const char* Ks, const bf16x8* qr, int r32, int hi, float negm) {
; #pragma unroll
;   for (int r = 0; r < 16; ++r) { p0[r] = negm; p1[r] = negm; }
; #pragma unroll
;   for (int d0 = 0; d0 < 6; ++d0) {
;     const bf16x8 b0 = *(const bf16x8*)(Ks + r32 * AT_KROW + d0 * 32 + hi * 16);
;     const bf16x8 b1 = *(const bf16x8*)(Ks + (32 + r32) * AT_KROW + d0 * 32 + hi * 16);
;     p0 = MFMA(b0, qr[d0], p0);
;     p1 = MFMA(b1, qr[d0], p1);
;   }
; }
; __device__ __forceinline__ int v_st(int k, int c) { const int kk = (k & ~0xC) | ((k & 4) << 1) | ((k & 8) >> 1); return ((kk >> 3) * 4 + (c >> 5)) * 512 + ((kk & 7) * 32 + (c & 31)) * 2; }
; __device__ __forceinline__ int v_rd_base(int lane) { return ((lane & 3) << 3) | (((lane >> 2) & 3) << 6) | (((lane >> 4) & 1) << 5) | (((lane >> 5) & 1) << 8); }
; template <int OFF> __device__ __forceinline__ s16x4 tr_read(int vb) {
;   s16x4 r; asm volatile("ds_read_b64_tr_b16 %0, %1 offset:%2" : "=&v"(r) : "v"(vb), "i"(OFF) : "memory"); return r;
; }
; template <int D0> __device__ __forceinline__ void pv_one(f32x16& od, int vb, bf16x8 pa0, bf16x8 pa1, bf16x8 pa2, bf16x8 pa3) {
;   const s16x4 l0 = tr_read<v_rd_off(D0, 0, 0)>(vb), h0 = tr_read<v_rd_off(D0, 0, 1)>(vb), l1 = tr_read<v_rd_off(D0, 1, 0)>(vb), h1 = tr_read<v_rd_off(D0, 1, 1)>(vb);
;   const s16x4 l2 = tr_read<v_rd_off(D0, 2, 0)>(vb), h2 = tr_read<v_rd_off(D0, 2, 1)>(vb), l3 = tr_read<v_rd_off(D0, 3, 0)>(vb), h3 = tr_read<v_rd_off(D0, 3, 1)>(vb);
;   asm volatile("s_waitcnt lgkmcnt(0)" ::: "memory"); SBAR();
;     ...
;   od = MFMA(pa0, PK(l0, h0), od);
;   od = MFMA(pa1, PK(l1, h1), od);
;   od = MFMA(pa2, PK(l2, h2), od);
;   od = MFMA(pa3, PK(l3, h3), od);
;     ...
; }
; __device__ void phase_attn(const Params& p, char* lds) {
;     ...
;       SBAR(); at_qkt(pA0, pA1, K_lds, qr, r32, hi, -m_reg);
;       at_finishSM(pB0, pB1, alB, l_reg, pa0, pa1, pa2, pa3); SBAR();
;       if (j + 3 < NT) SLOAD(0, (j + 3) * 64); SBAR();
;       pv_d0(o, vb0 + AT_SHMV, pa0, pa1, pa2, pa3); at_partialSM(pA0, pA1, m_reg, alA, false);
;       __syncthreads(); SWAIT(); SWRITE(1, 1);
;       RESC(alA); __syncthreads();
.Lat_rare2_back:
	v_add_f32_e32 v173, v173, v175
	v_cvt_pk_bf16_f32 v104, v32, v33
	v_cvt_pk_bf16_f32 v105, v34, v35
	v_cvt_pk_bf16_f32 v106, v36, v37
	v_cvt_pk_bf16_f32 v107, v38, v39
	v_cvt_pk_bf16_f32 v108, v40, v41
	v_cvt_pk_bf16_f32 v109, v42, v43
	v_cvt_pk_bf16_f32 v110, v44, v45
	v_cvt_pk_bf16_f32 v111, v46, v47
	v_cvt_pk_bf16_f32 v112, v48, v49
	v_cvt_pk_bf16_f32 v113, v50, v51
	v_cvt_pk_bf16_f32 v114, v52, v53
	v_cvt_pk_bf16_f32 v115, v54, v55
	v_cvt_pk_bf16_f32 v116, v56, v57
	v_cvt_pk_bf16_f32 v117, v58, v59
	v_cvt_pk_bf16_f32 v118, v60, v61
	v_cvt_pk_bf16_f32 v119, v62, v63
	ds_read_b128 v[184:187], v170 offset:0
	ds_read_b128 v[188:191], v170 offset:6656
	ds_read_b128 v[192:195], v170 offset:32
	ds_read_b128 v[196:199], v170 offset:6688
	s_barrier
	ds_read_b128 v[200:203], v170 offset:64
	ds_read_b128 v[204:207], v170 offset:6720
	s_waitcnt lgkmcnt(4)
	v_mfma_f32_32x32x16_bf16 v[32:47], v[184:187], v[80:83], v[64:79]
	v_mfma_f32_32x32x16_bf16 v[48:63], v[188:191], v[80:83], v[64:79]
	ds_read_b128 v[208:211], v170 offset:96
	ds_read_b128 v[212:215], v170 offset:6752
	s_waitcnt lgkmcnt(4)
	v_mfma_f32_32x32x16_bf16 v[32:47], v[192:195], v[84:87], v[32:47]
	v_mfma_f32_32x32x16_bf16 v[48:63], v[196:199], v[84:87], v[48:63]
	ds_read_b128 v[184:187], v170 offset:128
	ds_read_b128 v[188:191], v170 offset:6784
	s_waitcnt lgkmcnt(4)
	v_mfma_f32_32x32x16_bf16 v[32:47], v[200:203], v[88:91], v[32:47]
	v_mfma_f32_32x32x16_bf16 v[48:63], v[204:207], v[88:91], v[48:63]
	ds_read_b128 v[192:195], v170 offset:160
	ds_read_b128 v[196:199], v170 offset:6816
	s_waitcnt lgkmcnt(4)
	v_mfma_f32_32x32x16_bf16 v[32:47], v[208:211], v[92:95], v[32:47]
	v_mfma_f32_32x32x16_bf16 v[48:63], v[212:215], v[92:95], v[48:63]
	ds_read_b64_tr_b16 v[148:149], v171 offset:49152
	ds_read_b64_tr_b16 v[150:151], v171 offset:51200
	ds_read_b64_tr_b16 v[152:153], v171 offset:53248
	ds_read_b64_tr_b16 v[154:155], v171 offset:55296
	s_waitcnt lgkmcnt(6)
	v_mfma_f32_32x32x16_bf16 v[32:47], v[184:187], v[96:99], v[32:47]
	v_mfma_f32_32x32x16_bf16 v[48:63], v[188:191], v[96:99], v[48:63]
	ds_read_b64_tr_b16 v[156:157], v171 offset:57344
	ds_read_b64_tr_b16 v[158:159], v171 offset:59392
	ds_read_b64_tr_b16 v[216:217], v171 offset:61440
	ds_read_b64_tr_b16 v[218:219], v171 offset:63488
	s_waitcnt lgkmcnt(8)
	v_mfma_f32_32x32x16_bf16 v[32:47], v[192:195], v[100:103], v[32:47]
	v_mfma_f32_32x32x16_bf16 v[48:63], v[196:199], v[100:103], v[48:63]
	ds_read_b64_tr_b16 v[220:221], v171 offset:49664
	ds_read_b64_tr_b16 v[222:223], v171 offset:51712
	ds_read_b64_tr_b16 v[224:225], v171 offset:53760
	ds_read_b64_tr_b16 v[226:227], v171 offset:55808
	s_waitcnt lgkmcnt(10)
	v_mfma_f32_32x32x16_bf16 v[0:15], v[104:107], v[148:151], v[0:15]
	s_waitcnt lgkmcnt(8)
	v_mfma_f32_32x32x16_bf16 v[0:15], v[108:111], v[152:155], v[0:15]
	ds_read_b64_tr_b16 v[236:237], v171 offset:57856
	ds_read_b64_tr_b16 v[238:239], v171 offset:59904
	ds_read_b64_tr_b16 v[240:241], v171 offset:61952
	ds_read_b64_tr_b16 v[242:243], v171 offset:64000
	s_waitcnt lgkmcnt(10)
	v_mfma_f32_32x32x16_bf16 v[0:15], v[112:115], v[156:159], v[0:15]
	s_waitcnt lgkmcnt(8)
	v_mfma_f32_32x32x16_bf16 v[0:15], v[116:119], v[216:219], v[0:15]
	s_waitcnt lgkmcnt(6)
	v_mfma_f32_32x32x16_bf16 v[16:31], v[104:107], v[220:223], v[16:31]
	s_waitcnt lgkmcnt(4)
	v_mfma_f32_32x32x16_bf16 v[16:31], v[108:111], v[224:227], v[16:31]
	s_waitcnt lgkmcnt(2)
	v_mfma_f32_32x32x16_bf16 v[16:31], v[112:115], v[236:239], v[16:31]
	s_waitcnt lgkmcnt(0)
	v_mfma_f32_32x32x16_bf16 v[16:31], v[116:119], v[240:243], v[16:31]
	s_barrier
	s_waitcnt vmcnt(0)
	ds_write_b128 v167, v[120:123] offset:26624
	ds_write_b128 v169, v[132:135] offset:26624
	s_add_i32 m0, s40, 0x8000
	s_nop 0
	global_load_lds_dwordx4 v131, s[36:37]
	s_add_u32 s36, s36, 0x40000
	s_addc_u32 s37, s37, 0
	v_exp_f32_e32 v32, v32
	v_exp_f32_e32 v48, v48
	v_exp_f32_e32 v33, v33
	v_exp_f32_e32 v49, v49
	v_exp_f32_e32 v34, v34
	v_exp_f32_e32 v50, v50
	v_exp_f32_e32 v35, v35
	v_exp_f32_e32 v51, v51
	v_exp_f32_e32 v36, v36
	v_exp_f32_e32 v52, v52
	v_exp_f32_e32 v37, v37
	v_exp_f32_e32 v53, v53
	v_exp_f32_e32 v38, v38
	v_exp_f32_e32 v54, v54
	v_exp_f32_e32 v39, v39
	v_exp_f32_e32 v55, v55
	v_exp_f32_e32 v40, v40
	v_exp_f32_e32 v56, v56
	v_exp_f32_e32 v41, v41
	v_exp_f32_e32 v57, v57
	v_exp_f32_e32 v42, v42
	v_exp_f32_e32 v58, v58
	v_exp_f32_e32 v43, v43
	v_exp_f32_e32 v59, v59
	v_exp_f32_e32 v44, v44
	v_exp_f32_e32 v60, v60
	v_exp_f32_e32 v45, v45
	v_exp_f32_e32 v61, v61
	v_exp_f32_e32 v46, v46
	v_exp_f32_e32 v62, v62
	v_exp_f32_e32 v47, v47
	v_exp_f32_e32 v63, v63
	s_waitcnt lgkmcnt(0)
	global_load_dwordx4 v[120:123], v129, s[4:5]
	global_load_dwordx4 v[132:135], v130, s[6:7]
	s_add_u32 s4, s4, 0x40000
	s_addc_u32 s5, s5, 0
	s_add_u32 s6, s6, 0x1000
	s_addc_u32 s7, s7, 0
	v_add_f32_e32 v175, v32, v33
	v_add_f32_e32 v174, v48, v49
	v_add_f32_e32 v175, v175, v34
	v_add_f32_e32 v174, v174, v50
	v_add_f32_e32 v175, v175, v35
	v_add_f32_e32 v174, v174, v51
	v_add_f32_e32 v175, v175, v36
	v_add_f32_e32 v174, v174, v52
	v_add_f32_e32 v175, v175, v37
	v_add_f32_e32 v174, v174, v53
	v_add_f32_e32 v175, v175, v38
	v_add_f32_e32 v174, v174, v54
	v_add_f32_e32 v175, v175, v39
	v_add_f32_e32 v174, v174, v55
	v_add_f32_e32 v175, v175, v40
	v_add_f32_e32 v174, v174, v56
	v_add_f32_e32 v175, v175, v41
	v_add_f32_e32 v174, v174, v57
	v_add_f32_e32 v175, v175, v42
	v_add_f32_e32 v174, v174, v58
	v_add_f32_e32 v175, v175, v43
	v_add_f32_e32 v174, v174, v59
	v_add_f32_e32 v175, v175, v44
	v_add_f32_e32 v174, v174, v60
	v_add_f32_e32 v175, v175, v45
	v_add_f32_e32 v174, v174, v61
	v_add_f32_e32 v175, v175, v46
	v_add_f32_e32 v174, v174, v62
	v_add_f32_e32 v175, v175, v47
	v_add_f32_e32 v174, v174, v63
	v_add_f32_e32 v175, v175, v174
	v_cmp_ge_f32_e32 vcc, s23, v175
	s_cmp_eq_u64 vcc, exec
	s_cbranch_scc0 .Lat_rare3
; #define MFMA(a, b, c) __builtin_amdgcn_mfma_f32_32x32x16_bf16((a), (b), (c), 0, 0, 0)
; #define SBAR() __builtin_amdgcn_sched_barrier(0)
; __device__ __forceinline__ void at_qkt(f32x16& p0, f32x16& p1, const char* Ks, const bf16x8* qr, int r32, int hi, float negm) {
; #pragma unroll
;   for (int r = 0; r < 16; ++r) { p0[r] = negm; p1[r] = negm; }
; #pragma unroll
;   for (int d0 = 0; d0 < 6; ++d0) {
;     const bf16x8 b0 = *(const bf16x8*)(Ks + r32 * AT_KROW + d0 * 32 + hi * 16);
;     const bf16x8 b1 = *(const bf16x8*)(Ks + (32 + r32) * AT_KROW + d0 * 32 + hi * 16);
;     p0 = MFMA(b0, qr[d0], p0);
;     p1 = MFMA(b1, qr[d0], p1);
;   }
; }
; __device__ __forceinline__ int v_st(int k, int c) { const int kk = (k & ~0xC) | ((k & 4) << 1) | ((k & 8) >> 1); return ((kk >> 3) * 4 + (c >> 5)) * 512 + ((kk & 7) * 32 + (c & 31)) * 2; }
; __device__ __forceinline__ int v_rd_base(int lane) { return ((lane & 3) << 3) | (((lane >> 2) & 3) << 6) | (((lane >> 4) & 1) << 5) | (((lane >> 5) & 1) << 8); }
; template <int OFF> __device__ __forceinline__ s16x4 tr_read(int vb) {
;   s16x4 r; asm volatile("ds_read_b64_tr_b16 %0, %1 offset:%2" : "=&v"(r) : "v"(vb), "i"(OFF) : "memory"); return r;
; }
; template <int D0> __device__ __forceinline__ void pv_one(f32x16& od, int vb, bf16x8 pa0, bf16x8 pa1, bf16x8 pa2, bf16x8 pa3) {
;   const s16x4 l0 = tr_read<v_rd_off(D0, 0, 0)>(vb), h0 = tr_read<v_rd_off(D0, 0, 1)>(vb), l1 = tr_read<v_rd_off(D0, 1, 0)>(vb), h1 = tr_read<v_rd_off(D0, 1, 1)>(vb);
;   const s16x4 l2 = tr_read<v_rd_off(D0, 2, 0)>(vb), h2 = tr_read<v_rd_off(D0, 2, 1)>(vb), l3 = tr_read<v_rd_off(D0, 3, 0)>(vb), h3 = tr_read<v_rd_off(D0, 3, 1)>(vb);
;   asm volatile("s_waitcnt lgkmcnt(0)" ::: "memory"); SBAR();
;     ...
;   od = MFMA(pa0, PK(l0, h0), od);
;   od = MFMA(pa1, PK(l1, h1), od);
;   od = MFMA(pa2, PK(l2, h2), od);
;   od = MFMA(pa3, PK(l3, h3), od);
;     ...
; }
; __device__ void phase_attn(const Params& p, char* lds) {
;     ...
;       RESC(alA); __syncthreads();
;     }
;     SBAR(); at_qkt(pB0, pB1, K_lds + AT_SHMK, qr, r32, hi, -m_reg);
;     at_finishSM(pA0, pA1, alA, l_reg, pa0, pa1, pa2, pa3); SBAR();
;     pv_d0(o, vb0, pa0, pa1, pa2, pa3); at_partialSM(pB0, pB1, m_reg, alB, false);
;     __syncthreads(); RESC(alB);
.Lat_rare3_back:
	v_add_f32_e32 v173, v173, v175
	v_cvt_pk_bf16_f32 v104, v32, v33
	v_cvt_pk_bf16_f32 v105, v34, v35
	v_cvt_pk_bf16_f32 v106, v36, v37
	v_cvt_pk_bf16_f32 v107, v38, v39
	v_cvt_pk_bf16_f32 v108, v40, v41
	v_cvt_pk_bf16_f32 v109, v42, v43
	v_cvt_pk_bf16_f32 v110, v44, v45
	v_cvt_pk_bf16_f32 v111, v46, v47
	v_cvt_pk_bf16_f32 v112, v48, v49
	v_cvt_pk_bf16_f32 v113, v50, v51
	v_cvt_pk_bf16_f32 v114, v52, v53
	v_cvt_pk_bf16_f32 v115, v54, v55
	v_cvt_pk_bf16_f32 v116, v56, v57
	v_cvt_pk_bf16_f32 v117, v58, v59
	v_cvt_pk_bf16_f32 v118, v60, v61
	v_cvt_pk_bf16_f32 v119, v62, v63
	ds_read_b128 v[184:187], v170 offset:13312
	ds_read_b128 v[188:191], v170 offset:19968
	ds_read_b128 v[192:195], v170 offset:13344
	ds_read_b128 v[196:199], v170 offset:20000
	s_barrier
	s_sub_u32 s13, s13, 1
	s_cmp_lg_u32 s13, 0
	s_cbranch_scc1 .Lat_loop
	ds_read_b128 v[200:203], v170 offset:13376
	ds_read_b128 v[204:207], v170 offset:20032
	s_waitcnt lgkmcnt(4)
	v_mfma_f32_32x32x16_bf16 v[32:47], v[184:187], v[80:83], v[64:79]
	v_mfma_f32_32x32x16_bf16 v[48:63], v[188:191], v[80:83], v[64:79]
	ds_read_b128 v[208:211], v170 offset:13408
	ds_read_b128 v[212:215], v170 offset:20064
	s_waitcnt lgkmcnt(4)
	v_mfma_f32_32x32x16_bf16 v[32:47], v[192:195], v[84:87], v[32:47]
	v_mfma_f32_32x32x16_bf16 v[48:63], v[196:199], v[84:87], v[48:63]
	ds_read_b128 v[184:187], v170 offset:13440
	ds_read_b128 v[188:191], v170 offset:20096
	s_waitcnt lgkmcnt(4)
	v_mfma_f32_32x32x16_bf16 v[32:47], v[200:203], v[88:91], v[32:47]
	v_mfma_f32_32x32x16_bf16 v[48:63], v[204:207], v[88:91], v[48:63]
	ds_read_b128 v[192:195], v170 offset:13472
	ds_read_b128 v[196:199], v170 offset:20128
	s_waitcnt lgkmcnt(4)
	v_mfma_f32_32x32x16_bf16 v[32:47], v[208:211], v[92:95], v[32:47]
	v_mfma_f32_32x32x16_bf16 v[48:63], v[212:215], v[92:95], v[48:63]
	ds_read_b64_tr_b16 v[148:149], v171 offset:0
	ds_read_b64_tr_b16 v[150:151], v171 offset:2048
	ds_read_b64_tr_b16 v[152:153], v171 offset:4096
	ds_read_b64_tr_b16 v[154:155], v171 offset:6144
	s_waitcnt lgkmcnt(6)
	v_mfma_f32_32x32x16_bf16 v[32:47], v[184:187], v[96:99], v[32:47]
	v_mfma_f32_32x32x16_bf16 v[48:63], v[188:191], v[96:99], v[48:63]
	ds_read_b64_tr_b16 v[156:157], v171 offset:8192
	ds_read_b64_tr_b16 v[158:159], v171 offset:10240
	ds_read_b64_tr_b16 v[216:217], v171 offset:12288
	ds_read_b64_tr_b16 v[218:219], v171 offset:14336
	s_waitcnt lgkmcnt(8)
	v_mfma_f32_32x32x16_bf16 v[32:47], v[192:195], v[100:103], v[32:47]
	v_mfma_f32_32x32x16_bf16 v[48:63], v[196:199], v[100:103], v[48:63]
	ds_read_b64_tr_b16 v[220:221], v171 offset:512
	ds_read_b64_tr_b16 v[222:223], v171 offset:2560
	ds_read_b64_tr_b16 v[224:225], v171 offset:4608
	ds_read_b64_tr_b16 v[226:227], v171 offset:6656
	s_waitcnt lgkmcnt(10)
	v_mfma_f32_32x32x16_bf16 v[0:15], v[104:107], v[148:151], v[0:15]
	s_waitcnt lgkmcnt(8)
	v_mfma_f32_32x32x16_bf16 v[0:15], v[108:111], v[152:155], v[0:15]
	ds_read_b64_tr_b16 v[236:237], v171 offset:8704
	ds_read_b64_tr_b16 v[238:239], v171 offset:10752
	ds_read_b64_tr_b16 v[240:241], v171 offset:12800
	ds_read_b64_tr_b16 v[242:243], v171 offset:14848
	s_waitcnt lgkmcnt(10)
	v_mfma_f32_32x32x16_bf16 v[0:15], v[112:115], v[156:159], v[0:15]
	s_waitcnt lgkmcnt(8)
	v_mfma_f32_32x32x16_bf16 v[0:15], v[116:119], v[216:219], v[0:15]
	s_waitcnt lgkmcnt(6)
	v_mfma_f32_32x32x16_bf16 v[16:31], v[104:107], v[220:223], v[16:31]
	s_waitcnt lgkmcnt(4)
	v_mfma_f32_32x32x16_bf16 v[16:31], v[108:111], v[224:227], v[16:31]
	s_waitcnt lgkmcnt(2)
	v_mfma_f32_32x32x16_bf16 v[16:31], v[112:115], v[236:239], v[16:31]
	s_waitcnt lgkmcnt(0)
	v_mfma_f32_32x32x16_bf16 v[16:31], v[116:119], v[240:243], v[16:31]
	s_barrier
	s_waitcnt vmcnt(0)
	ds_write_b128 v167, v[120:123] offset:39936
	ds_write_b128 v169, v[132:135] offset:39936
	s_add_i32 m0, s40, 0xc000
	s_nop 0
	global_load_lds_dwordx4 v131, s[36:37]
	s_add_u32 s36, s36, 0x40000
	s_addc_u32 s37, s37, 0
	v_exp_f32_e32 v32, v32
	v_exp_f32_e32 v48, v48
	v_exp_f32_e32 v33, v33
	v_exp_f32_e32 v49, v49
	v_exp_f32_e32 v34, v34
	v_exp_f32_e32 v50, v50
	v_exp_f32_e32 v35, v35
	v_exp_f32_e32 v51, v51
	v_exp_f32_e32 v36, v36
	v_exp_f32_e32 v52, v52
	v_exp_f32_e32 v37, v37
	v_exp_f32_e32 v53, v53
	v_exp_f32_e32 v38, v38
	v_exp_f32_e32 v54, v54
	v_exp_f32_e32 v39, v39
	v_exp_f32_e32 v55, v55
	v_exp_f32_e32 v40, v40
	v_exp_f32_e32 v56, v56
	v_exp_f32_e32 v41, v41
	v_exp_f32_e32 v57, v57
	v_exp_f32_e32 v42, v42
	v_exp_f32_e32 v58, v58
	v_exp_f32_e32 v43, v43
	v_exp_f32_e32 v59, v59
	v_exp_f32_e32 v44, v44
	v_exp_f32_e32 v60, v60
	v_exp_f32_e32 v45, v45
	v_exp_f32_e32 v61, v61
	v_exp_f32_e32 v46, v46
	v_exp_f32_e32 v62, v62
	v_exp_f32_e32 v47, v47
	v_exp_f32_e32 v63, v63
	s_waitcnt lgkmcnt(0)
	v_add_f32_e32 v175, v32, v33
	v_add_f32_e32 v174, v48, v49
	v_add_f32_e32 v175, v175, v34
	v_add_f32_e32 v174, v174, v50
	v_add_f32_e32 v175, v175, v35
	v_add_f32_e32 v174, v174, v51
	v_add_f32_e32 v175, v175, v36
	v_add_f32_e32 v174, v174, v52
	v_add_f32_e32 v175, v175, v37
	v_add_f32_e32 v174, v174, v53
	v_add_f32_e32 v175, v175, v38
	v_add_f32_e32 v174, v174, v54
	v_add_f32_e32 v175, v175, v39
	v_add_f32_e32 v174, v174, v55
	v_add_f32_e32 v175, v175, v40
	v_add_f32_e32 v174, v174, v56
	v_add_f32_e32 v175, v175, v41
	v_add_f32_e32 v174, v174, v57
	v_add_f32_e32 v175, v175, v42
	v_add_f32_e32 v174, v174, v58
	v_add_f32_e32 v175, v175, v43
	v_add_f32_e32 v174, v174, v59
	v_add_f32_e32 v175, v175, v44
	v_add_f32_e32 v174, v174, v60
	v_add_f32_e32 v175, v175, v45
	v_add_f32_e32 v174, v174, v61
	v_add_f32_e32 v175, v175, v46
	v_add_f32_e32 v174, v174, v62
	v_add_f32_e32 v175, v175, v47
	v_add_f32_e32 v174, v174, v63
	v_add_f32_e32 v175, v175, v174
	v_cmp_ge_f32_e32 vcc, s23, v175
	s_cmp_eq_u64 vcc, exec
	s_cbranch_scc0 .Lat_rare_t129
; #define MFMA(a, b, c) __builtin_amdgcn_mfma_f32_32x32x16_bf16((a), (b), (c), 0, 0, 0)
; #define SBAR() __builtin_amdgcn_sched_barrier(0)
; __device__ __forceinline__ void at_qkt(f32x16& p0, f32x16& p1, const char* Ks, const bf16x8* qr, int r32, int hi, float negm) {
; #pragma unroll
;   for (int r = 0; r < 16; ++r) { p0[r] = negm; p1[r] = negm; }
; #pragma unroll
;   for (int d0 = 0; d0 < 6; ++d0) {
;     const bf16x8 b0 = *(const bf16x8*)(Ks + r32 * AT_KROW + d0 * 32 + hi * 16);
;     const bf16x8 b1 = *(const bf16x8*)(Ks + (32 + r32) * AT_KROW + d0 * 32 + hi * 16);
;     p0 = MFMA(b0, qr[d0], p0);
;     p1 = MFMA(b1, qr[d0], p1);
;   }
; }
; __device__ __forceinline__ int v_st(int k, int c) { const int kk = (k & ~0xC) | ((k & 4) << 1) | ((k & 8) >> 1); return ((kk >> 3) * 4 + (c >> 5)) * 512 + ((kk & 7) * 32 + (c & 31)) * 2; }
; __device__ __forceinline__ int v_rd_base(int lane) { return ((lane & 3) << 3) | (((lane >> 2) & 3) << 6) | (((lane >> 4) & 1) << 5) | (((lane >> 5) & 1) << 8); }
; template <int OFF> __device__ __forceinline__ s16x4 tr_read(int vb) {
;   s16x4 r; asm volatile("ds_read_b64_tr_b16 %0, %1 offset:%2" : "=&v"(r) : "v"(vb), "i"(OFF) : "memory"); return r;
; }
; template <int D0> __device__ __forceinline__ void pv_one(f32x16& od, int vb, bf16x8 pa0, bf16x8 pa1, bf16x8 pa2, bf16x8 pa3) {
;   const s16x4 l0 = tr_read<v_rd_off(D0, 0, 0)>(vb), h0 = tr_read<v_rd_off(D0, 0, 1)>(vb), l1 = tr_read<v_rd_off(D0, 1, 0)>(vb), h1 = tr_read<v_rd_off(D0, 1, 1)>(vb);
;   const s16x4 l2 = tr_read<v_rd_off(D0, 2, 0)>(vb), h2 = tr_read<v_rd_off(D0, 2, 1)>(vb), l3 = tr_read<v_rd_off(D0, 3, 0)>(vb), h3 = tr_read<v_rd_off(D0, 3, 1)>(vb);
;   asm volatile("s_waitcnt lgkmcnt(0)" ::: "memory"); SBAR();
;     ...
;   od = MFMA(pa0, PK(l0, h0), od);
;   od = MFMA(pa1, PK(l1, h1), od);
;   od = MFMA(pa2, PK(l2, h2), od);
;   od = MFMA(pa3, PK(l3, h3), od);
;     ...
; }
; __device__ void phase_attn(const Params& p, char* lds) {
;     ...
;     SBAR(); at_qkt(pB0, pB1, K_lds + AT_SHMK, qr, r32, hi, -m_reg);
;     at_finishSM(pA0, pA1, alA, l_reg, pa0, pa1, pa2, pa3); SBAR();
;     pv_d0(o, vb0, pa0, pa1, pa2, pa3); at_partialSM(pB0, pB1, m_reg, alB, false);
;     __syncthreads(); RESC(alB);
;     at_finishSM(pB0, pB1, alB, l_reg, pa0, pa1, pa2, pa3); SBAR();
;     pv_d0(o, vb0 + AT_SHMV, pa0, pa1, pa2, pa3);
.Lat_rare_t129_back:
	v_add_f32_e32 v173, v173, v175
	v_cvt_pk_bf16_f32 v104, v32, v33
	v_cvt_pk_bf16_f32 v105, v34, v35
	v_cvt_pk_bf16_f32 v106, v36, v37
	v_cvt_pk_bf16_f32 v107, v38, v39
	v_cvt_pk_bf16_f32 v108, v40, v41
	v_cvt_pk_bf16_f32 v109, v42, v43
	v_cvt_pk_bf16_f32 v110, v44, v45
	v_cvt_pk_bf16_f32 v111, v46, v47
	v_cvt_pk_bf16_f32 v112, v48, v49
	v_cvt_pk_bf16_f32 v113, v50, v51
	v_cvt_pk_bf16_f32 v114, v52, v53
	v_cvt_pk_bf16_f32 v115, v54, v55
	v_cvt_pk_bf16_f32 v116, v56, v57
	v_cvt_pk_bf16_f32 v117, v58, v59
	v_cvt_pk_bf16_f32 v118, v60, v61
	v_cvt_pk_bf16_f32 v119, v62, v63
	ds_read_b128 v[184:187], v170 offset:26624
	ds_read_b128 v[188:191], v170 offset:33280
	ds_read_b128 v[192:195], v170 offset:26656
	ds_read_b128 v[196:199], v170 offset:33312
	s_barrier
	ds_read_b128 v[200:203], v170 offset:26688
	ds_read_b128 v[204:207], v170 offset:33344
	s_waitcnt lgkmcnt(4)
	v_mfma_f32_32x32x16_bf16 v[32:47], v[184:187], v[80:83], v[64:79]
	v_mfma_f32_32x32x16_bf16 v[48:63], v[188:191], v[80:83], v[64:79]
	ds_read_b128 v[208:211], v170 offset:26720
	ds_read_b128 v[212:215], v170 offset:33376
	s_waitcnt lgkmcnt(4)
	v_mfma_f32_32x32x16_bf16 v[32:47], v[192:195], v[84:87], v[32:47]
	v_mfma_f32_32x32x16_bf16 v[48:63], v[196:199], v[84:87], v[48:63]
	ds_read_b128 v[184:187], v170 offset:26752
	ds_read_b128 v[188:191], v170 offset:33408
	s_waitcnt lgkmcnt(4)
	v_mfma_f32_32x32x16_bf16 v[32:47], v[200:203], v[88:91], v[32:47]
	v_mfma_f32_32x32x16_bf16 v[48:63], v[204:207], v[88:91], v[48:63]
	ds_read_b128 v[192:195], v170 offset:26784
	ds_read_b128 v[196:199], v170 offset:33440
	s_waitcnt lgkmcnt(4)
	v_mfma_f32_32x32x16_bf16 v[32:47], v[208:211], v[92:95], v[32:47]
	v_mfma_f32_32x32x16_bf16 v[48:63], v[212:215], v[92:95], v[48:63]
	ds_read_b64_tr_b16 v[148:149], v171 offset:16384
	ds_read_b64_tr_b16 v[150:151], v171 offset:18432
	ds_read_b64_tr_b16 v[152:153], v171 offset:20480
	ds_read_b64_tr_b16 v[154:155], v171 offset:22528
	s_waitcnt lgkmcnt(6)
	v_mfma_f32_32x32x16_bf16 v[32:47], v[184:187], v[96:99], v[32:47]
	v_mfma_f32_32x32x16_bf16 v[48:63], v[188:191], v[96:99], v[48:63]
	ds_read_b64_tr_b16 v[156:157], v171 offset:24576
	ds_read_b64_tr_b16 v[158:159], v171 offset:26624
	ds_read_b64_tr_b16 v[216:217], v171 offset:28672
	ds_read_b64_tr_b16 v[218:219], v171 offset:30720
	s_waitcnt lgkmcnt(8)
	v_mfma_f32_32x32x16_bf16 v[32:47], v[192:195], v[100:103], v[32:47]
	v_mfma_f32_32x32x16_bf16 v[48:63], v[196:199], v[100:103], v[48:63]
	ds_read_b64_tr_b16 v[220:221], v171 offset:16896
	ds_read_b64_tr_b16 v[222:223], v171 offset:18944
	ds_read_b64_tr_b16 v[224:225], v171 offset:20992
	ds_read_b64_tr_b16 v[226:227], v171 offset:23040
	s_waitcnt lgkmcnt(10)
	v_mfma_f32_32x32x16_bf16 v[0:15], v[104:107], v[148:151], v[0:15]
	s_waitcnt lgkmcnt(8)
	v_mfma_f32_32x32x16_bf16 v[0:15], v[108:111], v[152:155], v[0:15]
	ds_read_b64_tr_b16 v[236:237], v171 offset:25088
	ds_read_b64_tr_b16 v[238:239], v171 offset:27136
	ds_read_b64_tr_b16 v[240:241], v171 offset:29184
	ds_read_b64_tr_b16 v[242:243], v171 offset:31232
	s_waitcnt lgkmcnt(10)
	v_mfma_f32_32x32x16_bf16 v[0:15], v[112:115], v[156:159], v[0:15]
	s_waitcnt lgkmcnt(8)
	v_mfma_f32_32x32x16_bf16 v[0:15], v[116:119], v[216:219], v[0:15]
	s_waitcnt lgkmcnt(6)
	v_mfma_f32_32x32x16_bf16 v[16:31], v[104:107], v[220:223], v[16:31]
	s_waitcnt lgkmcnt(4)
	v_mfma_f32_32x32x16_bf16 v[16:31], v[108:111], v[224:227], v[16:31]
	s_waitcnt lgkmcnt(2)
	v_mfma_f32_32x32x16_bf16 v[16:31], v[112:115], v[236:239], v[16:31]
	s_waitcnt lgkmcnt(0)
	v_mfma_f32_32x32x16_bf16 v[16:31], v[116:119], v[240:243], v[16:31]
	s_barrier
	s_waitcnt vmcnt(0)
	v_exp_f32_e32 v32, v32
	v_exp_f32_e32 v48, v48
	v_exp_f32_e32 v33, v33
	v_exp_f32_e32 v49, v49
	v_exp_f32_e32 v34, v34
	v_exp_f32_e32 v50, v50
	v_exp_f32_e32 v35, v35
	v_exp_f32_e32 v51, v51
	v_exp_f32_e32 v36, v36
	v_exp_f32_e32 v52, v52
	v_exp_f32_e32 v37, v37
	v_exp_f32_e32 v53, v53
	v_exp_f32_e32 v38, v38
	v_exp_f32_e32 v54, v54
	v_exp_f32_e32 v39, v39
	v_exp_f32_e32 v55, v55
	v_exp_f32_e32 v40, v40
	v_exp_f32_e32 v56, v56
	v_exp_f32_e32 v41, v41
	v_exp_f32_e32 v57, v57
	v_exp_f32_e32 v42, v42
	v_exp_f32_e32 v58, v58
	v_exp_f32_e32 v43, v43
	v_exp_f32_e32 v59, v59
	v_exp_f32_e32 v44, v44
	v_exp_f32_e32 v60, v60
	v_exp_f32_e32 v45, v45
	v_exp_f32_e32 v61, v61
	v_exp_f32_e32 v46, v46
	v_exp_f32_e32 v62, v62
	v_exp_f32_e32 v47, v47
	v_exp_f32_e32 v63, v63
	v_add_f32_e32 v175, v32, v33
	v_add_f32_e32 v174, v48, v49
	v_add_f32_e32 v175, v175, v34
	v_add_f32_e32 v174, v174, v50
	v_add_f32_e32 v175, v175, v35
	v_add_f32_e32 v174, v174, v51
	v_add_f32_e32 v175, v175, v36
	v_add_f32_e32 v174, v174, v52
	v_add_f32_e32 v175, v175, v37
	v_add_f32_e32 v174, v174, v53
	v_add_f32_e32 v175, v175, v38
	v_add_f32_e32 v174, v174, v54
	v_add_f32_e32 v175, v175, v39
	v_add_f32_e32 v174, v174, v55
	v_add_f32_e32 v175, v175, v40
	v_add_f32_e32 v174, v174, v56
	v_add_f32_e32 v175, v175, v41
	v_add_f32_e32 v174, v174, v57
	v_add_f32_e32 v175, v175, v42
	v_add_f32_e32 v174, v174, v58
	v_add_f32_e32 v175, v175, v43
	v_add_f32_e32 v174, v174, v59
	v_add_f32_e32 v175, v175, v44
	v_add_f32_e32 v174, v174, v60
	v_add_f32_e32 v175, v175, v45
	v_add_f32_e32 v174, v174, v61
	v_add_f32_e32 v175, v175, v46
	v_add_f32_e32 v174, v174, v62
	v_add_f32_e32 v175, v175, v47
	v_add_f32_e32 v174, v174, v63
	v_add_f32_e32 v175, v175, v174
	v_cmp_ge_f32_e32 vcc, s23, v175
	s_cmp_eq_u64 vcc, exec
	s_cbranch_scc0 .Lat_rare_t130

; __device__ void phase_attn(const Params& p, char* lds) {
;     ...
;   }
; }
.Lat_done:
	s_mov_b32 m0, -1
